# SGU item: the 32 row loads of the LN-stats pass and the 16 per-token loads issued up front instead of serialized round trips
# speedup vs baseline: 1.0028x; 1.0028x over previous
; #define LAS __attribute__((address_space(3)))
; __device__ __forceinline__ float bf_lo(unsigned v) { return __uint_as_float(v << 16); }
; __device__ __forceinline__ float bf_hi(unsigned v) { return __uint_as_float(v & 0xffff0000u); }
; __device__ __forceinline__ int otid(int wv) { int l; asm volatile("v_mbcnt_lo_u32_b32 %0, -1, 0\n\tv_mbcnt_hi_u32_b32 %0, -1, %0" : "=v"(l)); return wv * 64 + l; }
; __device__ __forceinline__ void sgu_item(int it, const bf16_t* GV, const bf16_t* ZU, const float* sg_, const float* sb_, const float* wsp, const float* bsp, bf16_t* CAT, unsigned char* lds, const int wv) {
;     const int tid = otid(wv), wid = __builtin_amdgcn_readfirstlane(tid >> 6), lane = tid & 63;
;     const int chunk = it >> 3, g = it & 7, tok0 = chunk * 128;
;     LAS unsigned char* ZT = (LAS unsigned char*)lds;
;     __syncthreads();
;     {
;         float mean[16], rstd[16];
; #pragma unroll
;         for (int i = 0; i < 16; ++i) { const bf16_t* row = GV + (size_t)(tok0 + 16 * wid + i) * 1024;
;             const u32x4 a = *(const u32x4*)(row + 8 * lane), c = *(const u32x4*)(row + 512 + 8 * lane);
;             float v[16];
; #pragma unroll
;             for (int k = 0; k < 4; ++k) { v[2 * k] = bf_lo(a[k]); v[2 * k + 1] = bf_hi(a[k]); v[8 + 2 * k] = bf_lo(c[k]); v[8 + 2 * k + 1] = bf_hi(c[k]); }
;             float s = 0.f;
; #pragma unroll
;             for (int k = 0; k < 16; ++k) s += v[k];
;             const float mu = wave_sum(s) * (1.0f / 1024.0f); float q = 0.f;
; #pragma unroll
;             for (int k = 0; k < 16; ++k) { const float d = v[k] - mu; q += d * d; }
;             mean[i] = mu; rstd[i] = 1.0f / sqrtf(wave_sum(q) * (1.0f / 1024.0f) + EPS); }
.LBB0_288:
	v_mbcnt_lo_u32_b32 v16, -1, 0
	v_mbcnt_hi_u32_b32 v16, -1, v16
	s_waitcnt vmcnt(0)
	v_add_u32_e32 v0, s3, v16
	s_barrier
	v_readfirstlane_b32 s1, v0
	s_ashr_i32 s9, s1, 6
	s_and_b32 s1, s92, 0xffffff8
	s_add_i32 s1, s9, s1
	s_lshl_b32 s22, s1, 4
	s_ashr_i32 s23, s22, 31
	s_lshl_b64 s[16:17], s[22:23], 11
	v_and_b32_e32 v0, 63, v16
	s_add_u32 s4, s6, s16
	s_addc_u32 s5, s7, s17
	v_lshlrev_b32_e32 v3, 4, v0
	s_mov_b64 s[98:99], s[4:5]
	global_load_dwordx4 v[64:67], v3, s[98:99]
	global_load_dwordx4 v[68:71], v3, s[98:99] offset:1024
	global_load_dwordx4 v[72:75], v3, s[98:99] offset:2048
	global_load_dwordx4 v[76:79], v3, s[98:99] offset:3072
	s_add_u32 s98, s98, 0x1000
	s_addc_u32 s99, s99, 0
	global_load_dwordx4 v[80:83], v3, s[98:99]
	global_load_dwordx4 v[84:87], v3, s[98:99] offset:1024
	global_load_dwordx4 v[88:91], v3, s[98:99] offset:2048
	global_load_dwordx4 v[92:95], v3, s[98:99] offset:3072
	s_add_u32 s98, s98, 0x1000
	s_addc_u32 s99, s99, 0
	global_load_dwordx4 v[96:99], v3, s[98:99]
	global_load_dwordx4 v[100:103], v3, s[98:99] offset:1024
	global_load_dwordx4 v[104:107], v3, s[98:99] offset:2048
	global_load_dwordx4 v[108:111], v3, s[98:99] offset:3072
	s_add_u32 s98, s98, 0x1000
	s_addc_u32 s99, s99, 0
	global_load_dwordx4 v[112:115], v3, s[98:99]
	global_load_dwordx4 v[116:119], v3, s[98:99] offset:1024
	global_load_dwordx4 v[120:123], v3, s[98:99] offset:2048
	global_load_dwordx4 v[124:127], v3, s[98:99] offset:3072
	s_add_u32 s98, s98, 0x1000
	s_addc_u32 s99, s99, 0
	global_load_dwordx4 v[128:131], v3, s[98:99]
	global_load_dwordx4 v[132:135], v3, s[98:99] offset:1024
	global_load_dwordx4 v[136:139], v3, s[98:99] offset:2048
	global_load_dwordx4 v[140:143], v3, s[98:99] offset:3072
	s_add_u32 s98, s98, 0x1000
	s_addc_u32 s99, s99, 0
	global_load_dwordx4 v[144:147], v3, s[98:99]
	global_load_dwordx4 v[148:151], v3, s[98:99] offset:1024
	global_load_dwordx4 v[152:155], v3, s[98:99] offset:2048
	global_load_dwordx4 v[156:159], v3, s[98:99] offset:3072
	s_add_u32 s98, s98, 0x1000
	s_addc_u32 s99, s99, 0
	global_load_dwordx4 v[160:163], v3, s[98:99]
	global_load_dwordx4 v[164:167], v3, s[98:99] offset:1024
	global_load_dwordx4 v[168:171], v3, s[98:99] offset:2048
	global_load_dwordx4 v[172:175], v3, s[98:99] offset:3072
	s_add_u32 s98, s98, 0x1000
	s_addc_u32 s99, s99, 0
	global_load_dwordx4 v[176:179], v3, s[98:99]
	global_load_dwordx4 v[180:183], v3, s[98:99] offset:1024
	global_load_dwordx4 v[184:187], v3, s[98:99] offset:2048
	global_load_dwordx4 v[188:191], v3, s[98:99] offset:3072
	s_waitcnt vmcnt(30)
	v_mov_b32_e32 v4, v64
	v_mov_b32_e32 v5, v65
	v_mov_b32_e32 v6, v66
	v_mov_b32_e32 v7, v67
	v_mov_b32_e32 v8, v68
	v_mov_b32_e32 v9, v69
	v_mov_b32_e32 v10, v70
	v_mov_b32_e32 v11, v71
	v_lshlrev_b32_e32 v2, 16, v4
	v_and_b32_e32 v4, 0xffff0000, v4
	v_add_f32_e32 v1, 0, v2
	v_lshlrev_b32_e32 v13, 16, v5
	v_add_f32_e32 v1, v1, v4
	v_and_b32_e32 v5, 0xffff0000, v5
	v_add_f32_e32 v1, v1, v13
	v_lshlrev_b32_e32 v15, 16, v6
	v_add_f32_e32 v1, v1, v5
	v_and_b32_e32 v6, 0xffff0000, v6
	v_add_f32_e32 v1, v1, v15
	v_lshlrev_b32_e32 v18, 16, v7
	v_add_f32_e32 v1, v1, v6
	v_and_b32_e32 v7, 0xffff0000, v7
	v_add_f32_e32 v1, v1, v18
	v_lshlrev_b32_e32 v12, 16, v8
	v_add_f32_e32 v1, v1, v7
	v_and_b32_e32 v8, 0xffff0000, v8
	v_add_f32_e32 v1, v1, v12
	v_lshlrev_b32_e32 v14, 16, v9
	v_add_f32_e32 v1, v1, v8
	v_and_b32_e32 v9, 0xffff0000, v9
	v_add_f32_e32 v1, v1, v14
	v_lshlrev_b32_e32 v17, 16, v10
	v_add_f32_e32 v1, v1, v9
	v_and_b32_e32 v10, 0xffff0000, v10
	v_add_f32_e32 v1, v1, v17
	v_lshlrev_b32_e32 v19, 16, v11
	v_add_f32_e32 v1, v1, v10
	v_and_b32_e32 v11, 0xffff0000, v11
	v_add_f32_e32 v1, v1, v19
	v_add_f32_e32 v1, v1, v11
	s_nop 1
	v_add_f32_dpp v1, v1, v1 quad_perm:[1,0,3,2] row_mask:0xf bank_mask:0xf bound_ctrl:1
	s_nop 1
	v_add_f32_dpp v1, v1, v1 quad_perm:[2,3,0,1] row_mask:0xf bank_mask:0xf bound_ctrl:1
	s_nop 1
	v_add_f32_dpp v1, v1, v1 row_half_mirror row_mask:0xf bank_mask:0xf bound_ctrl:1
	s_nop 1
	v_add_f32_dpp v1, v1, v1 row_mirror row_mask:0xf bank_mask:0xf bound_ctrl:1
	ds_swizzle_b32 v20, v1 offset:swizzle(SWAP,16)
	s_waitcnt lgkmcnt(0)
	v_add_f32_e32 v1, v1, v20
	v_mov_b32_e32 v20, v1
	s_nop 1
	v_permlane32_swap_b32_e32 v1, v20
	v_add_f32_e32 v1, v1, v20
	v_fmac_f32_e32 v4, 0xba800000, v1
	v_fmac_f32_e32 v2, 0xba800000, v1
	v_mul_f32_e32 v4, v4, v4
	v_fmac_f32_e32 v4, v2, v2
	v_fmac_f32_e32 v13, 0xba800000, v1
	v_fmac_f32_e32 v4, v13, v13
	v_fmac_f32_e32 v5, 0xba800000, v1
	v_fmac_f32_e32 v4, v5, v5
	v_fmac_f32_e32 v15, 0xba800000, v1
	v_fmac_f32_e32 v4, v15, v15
	v_fmac_f32_e32 v6, 0xba800000, v1
	v_fmac_f32_e32 v4, v6, v6
	v_fmac_f32_e32 v18, 0xba800000, v1
	v_fmac_f32_e32 v4, v18, v18
	v_fmac_f32_e32 v7, 0xba800000, v1
	v_fmac_f32_e32 v4, v7, v7
	v_fmac_f32_e32 v12, 0xba800000, v1
	v_fmac_f32_e32 v4, v12, v12
	v_fmac_f32_e32 v8, 0xba800000, v1
	v_fmac_f32_e32 v4, v8, v8
	v_fmac_f32_e32 v14, 0xba800000, v1
	v_fmac_f32_e32 v4, v14, v14
	v_fmac_f32_e32 v9, 0xba800000, v1
	v_fmac_f32_e32 v4, v9, v9
	v_fmac_f32_e32 v17, 0xba800000, v1
	v_fmac_f32_e32 v4, v17, v17
	v_fmac_f32_e32 v10, 0xba800000, v1
	v_fmac_f32_e32 v4, v10, v10
	v_fmac_f32_e32 v19, 0xba800000, v1
	v_fmac_f32_e32 v4, v19, v19
	v_fmac_f32_e32 v11, 0xba800000, v1
	v_fmac_f32_e32 v4, v11, v11
	s_nop 1
	v_add_f32_dpp v2, v4, v4 quad_perm:[1,0,3,2] row_mask:0xf bank_mask:0xf bound_ctrl:1
	s_nop 1
	v_add_f32_dpp v2, v2, v2 quad_perm:[2,3,0,1] row_mask:0xf bank_mask:0xf bound_ctrl:1
	s_nop 1
	v_add_f32_dpp v2, v2, v2 row_half_mirror row_mask:0xf bank_mask:0xf bound_ctrl:1
	s_nop 1
	v_add_f32_dpp v2, v2, v2 row_mirror row_mask:0xf bank_mask:0xf bound_ctrl:1
	ds_swizzle_b32 v4, v2 offset:swizzle(SWAP,16)
	s_waitcnt lgkmcnt(0)
; __device__ __forceinline__ float bf_lo(unsigned v) { return __uint_as_float(v << 16); }
; __device__ __forceinline__ float bf_hi(unsigned v) { return __uint_as_float(v & 0xffff0000u); }
; __device__ __forceinline__ void sgu_item(int it, const bf16_t* GV, const bf16_t* ZU, const float* sg_, const float* sb_, const float* wsp, const float* bsp, bf16_t* CAT, unsigned char* lds, const int wv) {
;     ...
;         for (int i = 0; i < 16; ++i) { const bf16_t* row = GV + (size_t)(tok0 + 16 * wid + i) * 1024;
;             const u32x4 a = *(const u32x4*)(row + 8 * lane), c = *(const u32x4*)(row + 512 + 8 * lane);
;             float v[16];
; #pragma unroll
;             for (int k = 0; k < 4; ++k) { v[2 * k] = bf_lo(a[k]); v[2 * k + 1] = bf_hi(a[k]); v[8 + 2 * k] = bf_lo(c[k]); v[8 + 2 * k + 1] = bf_hi(c[k]); }
;             float s = 0.f;
; #pragma unroll
;             for (int k = 0; k < 16; ++k) s += v[k];
;             const float mu = wave_sum(s) * (1.0f / 1024.0f); float q = 0.f;
; #pragma unroll
;             for (int k = 0; k < 16; ++k) { const float d = v[k] - mu; q += d * d; }
;             mean[i] = mu; rstd[i] = 1.0f / sqrtf(wave_sum(q) * (1.0f / 1024.0f) + EPS); }
	v_add_f32_e32 v2, v2, v4
	v_mov_b32_e32 v4, v2
	s_nop 1
	v_permlane32_swap_b32_e32 v2, v4
	v_add_f32_e32 v2, v2, v4
	v_fmamk_f32 v2, v2, 0x3a800000, v244
	v_cmp_gt_f32_e32 vcc, s81, v2
	v_mul_f32_e32 v4, 0x4f800000, v2
	s_nop 0
	v_cndmask_b32_e32 v2, v2, v4, vcc
	v_sqrt_f32_e32 v4, v2
	s_nop 0
	v_add_u32_e32 v5, -1, v4
	v_fma_f32 v6, -v5, v4, v2
	v_cmp_ge_f32_e64 s[4:5], 0, v6
	v_add_u32_e32 v6, 1, v4
	s_nop 0
	v_cndmask_b32_e64 v5, v4, v5, s[4:5]
	v_fma_f32 v4, -v6, v4, v2
	v_cmp_lt_f32_e64 s[4:5], 0, v4
	s_nop 1
	v_cndmask_b32_e64 v4, v5, v6, s[4:5]
	v_mul_f32_e32 v5, 0x37800000, v4
	v_cndmask_b32_e32 v4, v4, v5, vcc
	v_cmp_class_f32_e32 vcc, v2, v245
	s_nop 1
	v_cndmask_b32_e32 v2, v4, v2, vcc
	v_div_scale_f32 v4, s[4:5], v2, v2, 1.0
	v_rcp_f32_e32 v5, v4
	s_or_b32 s4, s22, 1
	s_ashr_i32 s5, s4, 31
	s_lshl_b64 s[20:21], s[4:5], 11
	v_fma_f32 v6, -v4, v5, 1.0
	v_fmac_f32_e32 v5, v6, v5
	v_div_scale_f32 v6, vcc, 1.0, v2, 1.0
	v_mul_f32_e32 v7, v6, v5
	v_fma_f32 v8, -v4, v7, v6
	v_fmac_f32_e32 v7, v8, v5
	v_fma_f32 v4, -v4, v7, v6
	s_add_u32 s4, s6, s20
	v_div_fmas_f32 v4, v4, v5, v7
	s_addc_u32 s5, s7, s21
	v_div_fixup_f32 v2, v4, v2, 1.0
	s_waitcnt vmcnt(28)
	v_mov_b32_e32 v4, v72
	v_mov_b32_e32 v5, v73
	v_mov_b32_e32 v6, v74
	v_mov_b32_e32 v7, v75
	v_mov_b32_e32 v8, v76
	v_mov_b32_e32 v9, v77
	v_mov_b32_e32 v10, v78
	v_mov_b32_e32 v11, v79
	v_lshlrev_b32_e32 v12, 16, v4
	v_and_b32_e32 v13, 0xffff0000, v4
	v_add_f32_e32 v4, 0, v12
	v_lshlrev_b32_e32 v15, 16, v5
	v_add_f32_e32 v4, v4, v13
	v_and_b32_e32 v5, 0xffff0000, v5
	v_add_f32_e32 v4, v4, v15
	v_lshlrev_b32_e32 v18, 16, v6
	v_add_f32_e32 v4, v4, v5
	v_and_b32_e32 v6, 0xffff0000, v6
	v_add_f32_e32 v4, v4, v18
	v_lshlrev_b32_e32 v20, 16, v7
	v_add_f32_e32 v4, v4, v6
	v_and_b32_e32 v7, 0xffff0000, v7
	v_add_f32_e32 v4, v4, v20
	v_lshlrev_b32_e32 v14, 16, v8
	v_add_f32_e32 v4, v4, v7
	v_and_b32_e32 v8, 0xffff0000, v8
	v_add_f32_e32 v4, v4, v14
	v_lshlrev_b32_e32 v17, 16, v9
	v_add_f32_e32 v4, v4, v8
	v_and_b32_e32 v9, 0xffff0000, v9
	v_add_f32_e32 v4, v4, v17
	v_lshlrev_b32_e32 v19, 16, v10
	v_add_f32_e32 v4, v4, v9
	v_and_b32_e32 v10, 0xffff0000, v10
	v_add_f32_e32 v4, v4, v19
	v_lshlrev_b32_e32 v21, 16, v11
	v_add_f32_e32 v4, v4, v10
	v_and_b32_e32 v11, 0xffff0000, v11
	v_add_f32_e32 v4, v4, v21
	v_add_f32_e32 v4, v4, v11
	s_nop 1
	v_add_f32_dpp v4, v4, v4 quad_perm:[1,0,3,2] row_mask:0xf bank_mask:0xf bound_ctrl:1
	s_nop 1
	v_add_f32_dpp v4, v4, v4 quad_perm:[2,3,0,1] row_mask:0xf bank_mask:0xf bound_ctrl:1
	s_nop 1
	v_add_f32_dpp v4, v4, v4 row_half_mirror row_mask:0xf bank_mask:0xf bound_ctrl:1
	s_nop 1
	v_add_f32_dpp v4, v4, v4 row_mirror row_mask:0xf bank_mask:0xf bound_ctrl:1
	ds_swizzle_b32 v22, v4 offset:swizzle(SWAP,16)
	s_waitcnt lgkmcnt(0)
	v_add_f32_e32 v4, v4, v22
	v_mov_b32_e32 v22, v4
	s_nop 1
	v_permlane32_swap_b32_e32 v4, v22
	v_add_f32_e32 v4, v4, v22
	v_fmac_f32_e32 v13, 0xba800000, v4
	v_fmac_f32_e32 v12, 0xba800000, v4
	v_mul_f32_e32 v13, v13, v13
	v_fmac_f32_e32 v13, v12, v12
	v_fmac_f32_e32 v15, 0xba800000, v4
	v_fmac_f32_e32 v13, v15, v15
	v_fmac_f32_e32 v5, 0xba800000, v4
	v_fmac_f32_e32 v13, v5, v5
	v_fmac_f32_e32 v18, 0xba800000, v4
	v_fmac_f32_e32 v13, v18, v18
	v_fmac_f32_e32 v6, 0xba800000, v4
	v_fmac_f32_e32 v13, v6, v6
	v_fmac_f32_e32 v20, 0xba800000, v4
	v_fmac_f32_e32 v13, v20, v20
	v_fmac_f32_e32 v7, 0xba800000, v4
	v_fmac_f32_e32 v13, v7, v7
	v_fmac_f32_e32 v14, 0xba800000, v4
	v_fmac_f32_e32 v13, v14, v14
	v_fmac_f32_e32 v8, 0xba800000, v4
	v_fmac_f32_e32 v13, v8, v8
	v_fmac_f32_e32 v17, 0xba800000, v4
	v_fmac_f32_e32 v13, v17, v17
	v_fmac_f32_e32 v9, 0xba800000, v4
	v_fmac_f32_e32 v13, v9, v9
	v_fmac_f32_e32 v19, 0xba800000, v4
	v_fmac_f32_e32 v13, v19, v19
	v_fmac_f32_e32 v10, 0xba800000, v4
	v_fmac_f32_e32 v13, v10, v10
	v_fmac_f32_e32 v21, 0xba800000, v4
	v_fmac_f32_e32 v13, v21, v21
	v_fmac_f32_e32 v11, 0xba800000, v4
	v_fmac_f32_e32 v13, v11, v11
	s_nop 1
	v_add_f32_dpp v5, v13, v13 quad_perm:[1,0,3,2] row_mask:0xf bank_mask:0xf bound_ctrl:1
	s_nop 1
	v_add_f32_dpp v5, v5, v5 quad_perm:[2,3,0,1] row_mask:0xf bank_mask:0xf bound_ctrl:1
	s_nop 1
	v_add_f32_dpp v5, v5, v5 row_half_mirror row_mask:0xf bank_mask:0xf bound_ctrl:1
	s_nop 1
	v_add_f32_dpp v5, v5, v5 row_mirror row_mask:0xf bank_mask:0xf bound_ctrl:1
	ds_swizzle_b32 v6, v5 offset:swizzle(SWAP,16)
	s_waitcnt lgkmcnt(0)
	v_add_f32_e32 v5, v5, v6
	v_mov_b32_e32 v6, v5
	s_nop 1
	v_permlane32_swap_b32_e32 v5, v6
	v_add_f32_e32 v5, v5, v6
	v_fmamk_f32 v5, v5, 0x3a800000, v244
	v_cmp_gt_f32_e32 vcc, s81, v5
	v_mul_f32_e32 v6, 0x4f800000, v5
	s_nop 0
	v_cndmask_b32_e32 v5, v5, v6, vcc
	v_sqrt_f32_e32 v6, v5
	s_nop 0
	v_add_u32_e32 v7, -1, v6
	v_fma_f32 v8, -v7, v6, v5
	v_cmp_ge_f32_e64 s[4:5], 0, v8
	v_add_u32_e32 v8, 1, v6
	s_nop 0
	v_cndmask_b32_e64 v7, v6, v7, s[4:5]
	v_fma_f32 v6, -v8, v6, v5
	v_cmp_lt_f32_e64 s[4:5], 0, v6
	s_nop 1
	v_cndmask_b32_e64 v6, v7, v8, s[4:5]
	v_mul_f32_e32 v7, 0x37800000, v6
	v_cndmask_b32_e32 v6, v6, v7, vcc
	v_cmp_class_f32_e32 vcc, v5, v245
	s_nop 1
	v_cndmask_b32_e32 v5, v6, v5, vcc
	v_div_scale_f32 v6, s[4:5], v5, v5, 1.0
	v_rcp_f32_e32 v7, v6
	s_or_b32 s4, s22, 2
	s_ashr_i32 s5, s4, 31
	s_lshl_b64 s[28:29], s[4:5], 11
	v_fma_f32 v8, -v6, v7, 1.0
	v_fmac_f32_e32 v7, v8, v7
	v_div_scale_f32 v8, vcc, 1.0, v5, 1.0
	v_mul_f32_e32 v9, v8, v7
	v_fma_f32 v10, -v6, v9, v8
	v_fmac_f32_e32 v9, v10, v7
	v_fma_f32 v6, -v6, v9, v8
	s_add_u32 s4, s6, s28
	v_div_fmas_f32 v6, v6, v7, v9
	s_addc_u32 s5, s7, s29
	v_div_fixup_f32 v5, v6, v5, 1.0
	s_waitcnt vmcnt(26)
; __device__ __forceinline__ float bf_lo(unsigned v) { return __uint_as_float(v << 16); }
; __device__ __forceinline__ float bf_hi(unsigned v) { return __uint_as_float(v & 0xffff0000u); }
; __device__ __forceinline__ void sgu_item(int it, const bf16_t* GV, const bf16_t* ZU, const float* sg_, const float* sb_, const float* wsp, const float* bsp, bf16_t* CAT, unsigned char* lds, const int wv) {
;     ...
;         for (int i = 0; i < 16; ++i) { const bf16_t* row = GV + (size_t)(tok0 + 16 * wid + i) * 1024;
;             const u32x4 a = *(const u32x4*)(row + 8 * lane), c = *(const u32x4*)(row + 512 + 8 * lane);
;             float v[16];
; #pragma unroll
;             for (int k = 0; k < 4; ++k) { v[2 * k] = bf_lo(a[k]); v[2 * k + 1] = bf_hi(a[k]); v[8 + 2 * k] = bf_lo(c[k]); v[8 + 2 * k + 1] = bf_hi(c[k]); }
;             float s = 0.f;
; #pragma unroll
;             for (int k = 0; k < 16; ++k) s += v[k];
;             const float mu = wave_sum(s) * (1.0f / 1024.0f); float q = 0.f;
; #pragma unroll
;             for (int k = 0; k < 16; ++k) { const float d = v[k] - mu; q += d * d; }
;             mean[i] = mu; rstd[i] = 1.0f / sqrtf(wave_sum(q) * (1.0f / 1024.0f) + EPS); }
	v_mov_b32_e32 v6, v80
	v_mov_b32_e32 v7, v81
	v_mov_b32_e32 v8, v82
	v_mov_b32_e32 v9, v83
	v_mov_b32_e32 v10, v84
	v_mov_b32_e32 v11, v85
	v_mov_b32_e32 v12, v86
	v_mov_b32_e32 v13, v87
	v_lshlrev_b32_e32 v14, 16, v6
	v_and_b32_e32 v15, 0xffff0000, v6
	v_add_f32_e32 v6, 0, v14
	v_lshlrev_b32_e32 v18, 16, v7
	v_add_f32_e32 v6, v6, v15
	v_and_b32_e32 v7, 0xffff0000, v7
	v_add_f32_e32 v6, v6, v18
	v_lshlrev_b32_e32 v20, 16, v8
	v_add_f32_e32 v6, v6, v7
	v_and_b32_e32 v8, 0xffff0000, v8
	v_add_f32_e32 v6, v6, v20
	v_lshlrev_b32_e32 v22, 16, v9
	v_add_f32_e32 v6, v6, v8
	v_and_b32_e32 v9, 0xffff0000, v9
	v_add_f32_e32 v6, v6, v22
	v_lshlrev_b32_e32 v17, 16, v10
	v_add_f32_e32 v6, v6, v9
	v_and_b32_e32 v10, 0xffff0000, v10
	v_add_f32_e32 v6, v6, v17
	v_lshlrev_b32_e32 v19, 16, v11
	v_add_f32_e32 v6, v6, v10
	v_and_b32_e32 v11, 0xffff0000, v11
	v_add_f32_e32 v6, v6, v19
	v_lshlrev_b32_e32 v21, 16, v12
	v_add_f32_e32 v6, v6, v11
	v_and_b32_e32 v12, 0xffff0000, v12
	v_add_f32_e32 v6, v6, v21
	v_lshlrev_b32_e32 v23, 16, v13
	v_add_f32_e32 v6, v6, v12
	v_and_b32_e32 v13, 0xffff0000, v13
	v_add_f32_e32 v6, v6, v23
	v_add_f32_e32 v6, v6, v13
	s_nop 1
	v_add_f32_dpp v6, v6, v6 quad_perm:[1,0,3,2] row_mask:0xf bank_mask:0xf bound_ctrl:1
	s_nop 1
	v_add_f32_dpp v6, v6, v6 quad_perm:[2,3,0,1] row_mask:0xf bank_mask:0xf bound_ctrl:1
	s_nop 1
	v_add_f32_dpp v6, v6, v6 row_half_mirror row_mask:0xf bank_mask:0xf bound_ctrl:1
	s_nop 1
	v_add_f32_dpp v6, v6, v6 row_mirror row_mask:0xf bank_mask:0xf bound_ctrl:1
	ds_swizzle_b32 v24, v6 offset:swizzle(SWAP,16)
	s_waitcnt lgkmcnt(0)
	v_add_f32_e32 v6, v6, v24
	v_mov_b32_e32 v24, v6
	s_nop 1
	v_permlane32_swap_b32_e32 v6, v24
	v_add_f32_e32 v6, v6, v24
	v_fmac_f32_e32 v15, 0xba800000, v6
	v_fmac_f32_e32 v14, 0xba800000, v6
	v_mul_f32_e32 v15, v15, v15
	v_fmac_f32_e32 v15, v14, v14
	v_fmac_f32_e32 v18, 0xba800000, v6
	v_fmac_f32_e32 v15, v18, v18
	v_fmac_f32_e32 v7, 0xba800000, v6
	v_fmac_f32_e32 v15, v7, v7
	v_fmac_f32_e32 v20, 0xba800000, v6
	v_fmac_f32_e32 v15, v20, v20
	v_fmac_f32_e32 v8, 0xba800000, v6
	v_fmac_f32_e32 v15, v8, v8
	v_fmac_f32_e32 v22, 0xba800000, v6
	v_fmac_f32_e32 v15, v22, v22
	v_fmac_f32_e32 v9, 0xba800000, v6
	v_fmac_f32_e32 v15, v9, v9
	v_fmac_f32_e32 v17, 0xba800000, v6
	v_fmac_f32_e32 v15, v17, v17
	v_fmac_f32_e32 v10, 0xba800000, v6
	v_fmac_f32_e32 v15, v10, v10
	v_fmac_f32_e32 v19, 0xba800000, v6
	v_fmac_f32_e32 v15, v19, v19
	v_fmac_f32_e32 v11, 0xba800000, v6
	v_fmac_f32_e32 v15, v11, v11
	v_fmac_f32_e32 v21, 0xba800000, v6
	v_fmac_f32_e32 v15, v21, v21
	v_fmac_f32_e32 v12, 0xba800000, v6
	v_fmac_f32_e32 v15, v12, v12
	v_fmac_f32_e32 v23, 0xba800000, v6
	v_fmac_f32_e32 v15, v23, v23
	v_fmac_f32_e32 v13, 0xba800000, v6
	v_fmac_f32_e32 v15, v13, v13
	s_nop 1
	v_add_f32_dpp v7, v15, v15 quad_perm:[1,0,3,2] row_mask:0xf bank_mask:0xf bound_ctrl:1
	s_nop 1
	v_add_f32_dpp v7, v7, v7 quad_perm:[2,3,0,1] row_mask:0xf bank_mask:0xf bound_ctrl:1
	s_nop 1
	v_add_f32_dpp v7, v7, v7 row_half_mirror row_mask:0xf bank_mask:0xf bound_ctrl:1
	s_nop 1
	v_add_f32_dpp v7, v7, v7 row_mirror row_mask:0xf bank_mask:0xf bound_ctrl:1
	ds_swizzle_b32 v8, v7 offset:swizzle(SWAP,16)
	s_waitcnt lgkmcnt(0)
	v_add_f32_e32 v7, v7, v8
	v_mov_b32_e32 v8, v7
	s_nop 1
	v_permlane32_swap_b32_e32 v7, v8
	v_add_f32_e32 v7, v7, v8
	v_fmamk_f32 v7, v7, 0x3a800000, v244
	v_cmp_gt_f32_e32 vcc, s81, v7
	v_mul_f32_e32 v8, 0x4f800000, v7
	s_nop 0
	v_cndmask_b32_e32 v7, v7, v8, vcc
	v_sqrt_f32_e32 v8, v7
	s_nop 0
	v_add_u32_e32 v9, -1, v8
	v_fma_f32 v10, -v9, v8, v7
	v_cmp_ge_f32_e64 s[4:5], 0, v10
	v_add_u32_e32 v10, 1, v8
	s_nop 0
	v_cndmask_b32_e64 v9, v8, v9, s[4:5]
	v_fma_f32 v8, -v10, v8, v7
	v_cmp_lt_f32_e64 s[4:5], 0, v8
	s_nop 1
	v_cndmask_b32_e64 v8, v9, v10, s[4:5]
	v_mul_f32_e32 v9, 0x37800000, v8
	v_cndmask_b32_e32 v8, v8, v9, vcc
	v_cmp_class_f32_e32 vcc, v7, v245
	s_nop 1
	v_cndmask_b32_e32 v7, v8, v7, vcc
	v_div_scale_f32 v8, s[4:5], v7, v7, 1.0
	v_rcp_f32_e32 v9, v8
	s_or_b32 s4, s22, 3
	s_ashr_i32 s5, s4, 31
	s_lshl_b64 s[30:31], s[4:5], 11
	v_fma_f32 v10, -v8, v9, 1.0
	v_fmac_f32_e32 v9, v10, v9
	v_div_scale_f32 v10, vcc, 1.0, v7, 1.0
	v_mul_f32_e32 v11, v10, v9
	v_fma_f32 v12, -v8, v11, v10
	v_fmac_f32_e32 v11, v12, v9
	v_fma_f32 v8, -v8, v11, v10
	s_add_u32 s4, s6, s30
	v_div_fmas_f32 v8, v8, v9, v11
	s_addc_u32 s5, s7, s31
	v_div_fixup_f32 v7, v8, v7, 1.0
	s_waitcnt vmcnt(24)
	v_mov_b32_e32 v8, v88
	v_mov_b32_e32 v9, v89
	v_mov_b32_e32 v10, v90
	v_mov_b32_e32 v11, v91
	v_mov_b32_e32 v12, v92
	v_mov_b32_e32 v13, v93
	v_mov_b32_e32 v14, v94
	v_mov_b32_e32 v15, v95
	v_lshlrev_b32_e32 v17, 16, v8
	v_and_b32_e32 v18, 0xffff0000, v8
	v_add_f32_e32 v8, 0, v17
	v_lshlrev_b32_e32 v20, 16, v9
	v_add_f32_e32 v8, v8, v18
	v_and_b32_e32 v9, 0xffff0000, v9
	v_add_f32_e32 v8, v8, v20
	v_lshlrev_b32_e32 v22, 16, v10
	v_add_f32_e32 v8, v8, v9
	v_and_b32_e32 v10, 0xffff0000, v10
	v_add_f32_e32 v8, v8, v22
	v_lshlrev_b32_e32 v24, 16, v11
	v_add_f32_e32 v8, v8, v10
	v_and_b32_e32 v11, 0xffff0000, v11
	v_add_f32_e32 v8, v8, v24
	v_lshlrev_b32_e32 v19, 16, v12
	v_add_f32_e32 v8, v8, v11
	v_and_b32_e32 v12, 0xffff0000, v12
	v_add_f32_e32 v8, v8, v19
	v_lshlrev_b32_e32 v21, 16, v13
	v_add_f32_e32 v8, v8, v12
	v_and_b32_e32 v13, 0xffff0000, v13
	v_add_f32_e32 v8, v8, v21
	v_lshlrev_b32_e32 v23, 16, v14
	v_add_f32_e32 v8, v8, v13
	v_and_b32_e32 v14, 0xffff0000, v14
	v_add_f32_e32 v8, v8, v23
	v_lshlrev_b32_e32 v25, 16, v15
	v_add_f32_e32 v8, v8, v14
	v_and_b32_e32 v15, 0xffff0000, v15
	v_add_f32_e32 v8, v8, v25
	v_add_f32_e32 v8, v8, v15
	s_nop 1
	v_add_f32_dpp v8, v8, v8 quad_perm:[1,0,3,2] row_mask:0xf bank_mask:0xf bound_ctrl:1
	s_nop 1
	v_add_f32_dpp v8, v8, v8 quad_perm:[2,3,0,1] row_mask:0xf bank_mask:0xf bound_ctrl:1
	s_nop 1
	v_add_f32_dpp v8, v8, v8 row_half_mirror row_mask:0xf bank_mask:0xf bound_ctrl:1
	s_nop 1
	v_add_f32_dpp v8, v8, v8 row_mirror row_mask:0xf bank_mask:0xf bound_ctrl:1
	ds_swizzle_b32 v26, v8 offset:swizzle(SWAP,16)
	s_waitcnt lgkmcnt(0)
; __device__ __forceinline__ float bf_lo(unsigned v) { return __uint_as_float(v << 16); }
; __device__ __forceinline__ float bf_hi(unsigned v) { return __uint_as_float(v & 0xffff0000u); }
; __device__ __forceinline__ void sgu_item(int it, const bf16_t* GV, const bf16_t* ZU, const float* sg_, const float* sb_, const float* wsp, const float* bsp, bf16_t* CAT, unsigned char* lds, const int wv) {
;     ...
;         for (int i = 0; i < 16; ++i) { const bf16_t* row = GV + (size_t)(tok0 + 16 * wid + i) * 1024;
;             const u32x4 a = *(const u32x4*)(row + 8 * lane), c = *(const u32x4*)(row + 512 + 8 * lane);
;             float v[16];
; #pragma unroll
;             for (int k = 0; k < 4; ++k) { v[2 * k] = bf_lo(a[k]); v[2 * k + 1] = bf_hi(a[k]); v[8 + 2 * k] = bf_lo(c[k]); v[8 + 2 * k + 1] = bf_hi(c[k]); }
;             float s = 0.f;
; #pragma unroll
;             for (int k = 0; k < 16; ++k) s += v[k];
;             const float mu = wave_sum(s) * (1.0f / 1024.0f); float q = 0.f;
; #pragma unroll
;             for (int k = 0; k < 16; ++k) { const float d = v[k] - mu; q += d * d; }
;             mean[i] = mu; rstd[i] = 1.0f / sqrtf(wave_sum(q) * (1.0f / 1024.0f) + EPS); }
	v_add_f32_e32 v8, v8, v26
	v_mov_b32_e32 v26, v8
	s_nop 1
	v_permlane32_swap_b32_e32 v8, v26
	v_add_f32_e32 v8, v8, v26
	v_fmac_f32_e32 v18, 0xba800000, v8
	v_fmac_f32_e32 v17, 0xba800000, v8
	v_mul_f32_e32 v18, v18, v18
	v_fmac_f32_e32 v18, v17, v17
	v_fmac_f32_e32 v20, 0xba800000, v8
	v_fmac_f32_e32 v18, v20, v20
	v_fmac_f32_e32 v9, 0xba800000, v8
	v_fmac_f32_e32 v18, v9, v9
	v_fmac_f32_e32 v22, 0xba800000, v8
	v_fmac_f32_e32 v18, v22, v22
	v_fmac_f32_e32 v10, 0xba800000, v8
	v_fmac_f32_e32 v18, v10, v10
	v_fmac_f32_e32 v24, 0xba800000, v8
	v_fmac_f32_e32 v18, v24, v24
	v_fmac_f32_e32 v11, 0xba800000, v8
	v_fmac_f32_e32 v18, v11, v11
	v_fmac_f32_e32 v19, 0xba800000, v8
	v_fmac_f32_e32 v18, v19, v19
	v_fmac_f32_e32 v12, 0xba800000, v8
	v_fmac_f32_e32 v18, v12, v12
	v_fmac_f32_e32 v21, 0xba800000, v8
	v_fmac_f32_e32 v18, v21, v21
	v_fmac_f32_e32 v13, 0xba800000, v8
	v_fmac_f32_e32 v18, v13, v13
	v_fmac_f32_e32 v23, 0xba800000, v8
	v_fmac_f32_e32 v18, v23, v23
	v_fmac_f32_e32 v14, 0xba800000, v8
	v_fmac_f32_e32 v18, v14, v14
	v_fmac_f32_e32 v25, 0xba800000, v8
	v_fmac_f32_e32 v18, v25, v25
	v_fmac_f32_e32 v15, 0xba800000, v8
	v_fmac_f32_e32 v18, v15, v15
	s_nop 1
	v_add_f32_dpp v9, v18, v18 quad_perm:[1,0,3,2] row_mask:0xf bank_mask:0xf bound_ctrl:1
	s_nop 1
	v_add_f32_dpp v9, v9, v9 quad_perm:[2,3,0,1] row_mask:0xf bank_mask:0xf bound_ctrl:1
	s_nop 1
	v_add_f32_dpp v9, v9, v9 row_half_mirror row_mask:0xf bank_mask:0xf bound_ctrl:1
	s_nop 1
	v_add_f32_dpp v9, v9, v9 row_mirror row_mask:0xf bank_mask:0xf bound_ctrl:1
	ds_swizzle_b32 v10, v9 offset:swizzle(SWAP,16)
	s_waitcnt lgkmcnt(0)
	v_add_f32_e32 v9, v9, v10
	v_mov_b32_e32 v10, v9
	s_nop 1
	v_permlane32_swap_b32_e32 v9, v10
	v_add_f32_e32 v9, v9, v10
	v_fmamk_f32 v9, v9, 0x3a800000, v244
	v_cmp_gt_f32_e32 vcc, s81, v9
	v_mul_f32_e32 v10, 0x4f800000, v9
	s_nop 0
	v_cndmask_b32_e32 v9, v9, v10, vcc
	v_sqrt_f32_e32 v10, v9
	s_nop 0
	v_add_u32_e32 v11, -1, v10
	v_fma_f32 v12, -v11, v10, v9
	v_cmp_ge_f32_e64 s[4:5], 0, v12
	v_add_u32_e32 v12, 1, v10
	s_nop 0
	v_cndmask_b32_e64 v11, v10, v11, s[4:5]
	v_fma_f32 v10, -v12, v10, v9
	v_cmp_lt_f32_e64 s[4:5], 0, v10
	s_nop 1
	v_cndmask_b32_e64 v10, v11, v12, s[4:5]
	v_mul_f32_e32 v11, 0x37800000, v10
	v_cndmask_b32_e32 v10, v10, v11, vcc
	v_cmp_class_f32_e32 vcc, v9, v245
	s_nop 1
	v_cndmask_b32_e32 v9, v10, v9, vcc
	v_div_scale_f32 v10, s[4:5], v9, v9, 1.0
	v_rcp_f32_e32 v11, v10
	s_or_b32 s4, s22, 4
	s_ashr_i32 s5, s4, 31
	s_lshl_b64 s[34:35], s[4:5], 11
	v_fma_f32 v12, -v10, v11, 1.0
	v_fmac_f32_e32 v11, v12, v11
	v_div_scale_f32 v12, vcc, 1.0, v9, 1.0
	v_mul_f32_e32 v13, v12, v11
	v_fma_f32 v14, -v10, v13, v12
	v_fmac_f32_e32 v13, v14, v11
	v_fma_f32 v10, -v10, v13, v12
	s_add_u32 s4, s6, s34
	v_div_fmas_f32 v10, v10, v11, v13
	s_addc_u32 s5, s7, s35
	v_div_fixup_f32 v9, v10, v9, 1.0
	s_waitcnt vmcnt(22)
	v_mov_b32_e32 v10, v96
	v_mov_b32_e32 v11, v97
	v_mov_b32_e32 v12, v98
	v_mov_b32_e32 v13, v99
	v_mov_b32_e32 v18, v100
	v_mov_b32_e32 v19, v101
	v_mov_b32_e32 v20, v102
	v_mov_b32_e32 v21, v103
	v_lshlrev_b32_e32 v14, 16, v10
	v_and_b32_e32 v15, 0xffff0000, v10
	v_add_f32_e32 v10, 0, v14
	v_lshlrev_b32_e32 v22, 16, v11
	v_add_f32_e32 v10, v10, v15
	v_and_b32_e32 v11, 0xffff0000, v11
	v_add_f32_e32 v10, v10, v22
	v_lshlrev_b32_e32 v24, 16, v12
	v_add_f32_e32 v10, v10, v11
	v_and_b32_e32 v12, 0xffff0000, v12
	v_add_f32_e32 v10, v10, v24
	v_lshlrev_b32_e32 v26, 16, v13
	v_add_f32_e32 v10, v10, v12
	v_and_b32_e32 v13, 0xffff0000, v13
	v_add_f32_e32 v10, v10, v26
	v_lshlrev_b32_e32 v17, 16, v18
	v_add_f32_e32 v10, v10, v13
	v_and_b32_e32 v18, 0xffff0000, v18
	v_add_f32_e32 v10, v10, v17
	v_lshlrev_b32_e32 v23, 16, v19
	v_add_f32_e32 v10, v10, v18
	v_and_b32_e32 v19, 0xffff0000, v19
	v_add_f32_e32 v10, v10, v23
	v_lshlrev_b32_e32 v25, 16, v20
	v_add_f32_e32 v10, v10, v19
	v_and_b32_e32 v20, 0xffff0000, v20
	v_add_f32_e32 v10, v10, v25
	v_lshlrev_b32_e32 v27, 16, v21
	v_add_f32_e32 v10, v10, v20
	v_and_b32_e32 v21, 0xffff0000, v21
	v_add_f32_e32 v10, v10, v27
	v_add_f32_e32 v10, v10, v21
	s_nop 1
	v_add_f32_dpp v10, v10, v10 quad_perm:[1,0,3,2] row_mask:0xf bank_mask:0xf bound_ctrl:1
	s_nop 1
	v_add_f32_dpp v10, v10, v10 quad_perm:[2,3,0,1] row_mask:0xf bank_mask:0xf bound_ctrl:1
	s_nop 1
	v_add_f32_dpp v10, v10, v10 row_half_mirror row_mask:0xf bank_mask:0xf bound_ctrl:1
	s_nop 1
	v_add_f32_dpp v10, v10, v10 row_mirror row_mask:0xf bank_mask:0xf bound_ctrl:1
	ds_swizzle_b32 v28, v10 offset:swizzle(SWAP,16)
	s_waitcnt lgkmcnt(0)
	v_add_f32_e32 v10, v10, v28
	v_mov_b32_e32 v28, v10
	s_nop 1
	v_permlane32_swap_b32_e32 v10, v28
	v_add_f32_e32 v10, v10, v28
	v_fmac_f32_e32 v15, 0xba800000, v10
	v_fmac_f32_e32 v14, 0xba800000, v10
	v_mul_f32_e32 v15, v15, v15
	v_fmac_f32_e32 v15, v14, v14
	v_fmac_f32_e32 v22, 0xba800000, v10
	v_fmac_f32_e32 v15, v22, v22
	v_fmac_f32_e32 v11, 0xba800000, v10
	v_fmac_f32_e32 v15, v11, v11
	v_fmac_f32_e32 v24, 0xba800000, v10
	v_fmac_f32_e32 v15, v24, v24
	v_fmac_f32_e32 v12, 0xba800000, v10
	v_fmac_f32_e32 v15, v12, v12
	v_fmac_f32_e32 v26, 0xba800000, v10
	v_fmac_f32_e32 v15, v26, v26
	v_fmac_f32_e32 v13, 0xba800000, v10
	v_fmac_f32_e32 v15, v13, v13
	v_fmac_f32_e32 v17, 0xba800000, v10
	v_fmac_f32_e32 v15, v17, v17
	v_fmac_f32_e32 v18, 0xba800000, v10
	v_fmac_f32_e32 v15, v18, v18
	v_fmac_f32_e32 v23, 0xba800000, v10
	v_fmac_f32_e32 v15, v23, v23
	v_fmac_f32_e32 v19, 0xba800000, v10
	v_fmac_f32_e32 v15, v19, v19
	v_fmac_f32_e32 v25, 0xba800000, v10
	v_fmac_f32_e32 v15, v25, v25
	v_fmac_f32_e32 v20, 0xba800000, v10
	v_fmac_f32_e32 v15, v20, v20
	v_fmac_f32_e32 v27, 0xba800000, v10
	v_fmac_f32_e32 v15, v27, v27
	v_fmac_f32_e32 v21, 0xba800000, v10
	v_fmac_f32_e32 v15, v21, v21
	s_nop 1
	v_add_f32_dpp v11, v15, v15 quad_perm:[1,0,3,2] row_mask:0xf bank_mask:0xf bound_ctrl:1
	s_nop 1
	v_add_f32_dpp v11, v11, v11 quad_perm:[2,3,0,1] row_mask:0xf bank_mask:0xf bound_ctrl:1
	s_nop 1
	v_add_f32_dpp v11, v11, v11 row_half_mirror row_mask:0xf bank_mask:0xf bound_ctrl:1
	s_nop 1
	v_add_f32_dpp v11, v11, v11 row_mirror row_mask:0xf bank_mask:0xf bound_ctrl:1
	ds_swizzle_b32 v12, v11 offset:swizzle(SWAP,16)
	s_waitcnt lgkmcnt(0)
; __device__ __forceinline__ float bf_lo(unsigned v) { return __uint_as_float(v << 16); }
; __device__ __forceinline__ float bf_hi(unsigned v) { return __uint_as_float(v & 0xffff0000u); }
; __device__ __forceinline__ void sgu_item(int it, const bf16_t* GV, const bf16_t* ZU, const float* sg_, const float* sb_, const float* wsp, const float* bsp, bf16_t* CAT, unsigned char* lds, const int wv) {
;     ...
;         for (int i = 0; i < 16; ++i) { const bf16_t* row = GV + (size_t)(tok0 + 16 * wid + i) * 1024;
;             const u32x4 a = *(const u32x4*)(row + 8 * lane), c = *(const u32x4*)(row + 512 + 8 * lane);
;             float v[16];
; #pragma unroll
;             for (int k = 0; k < 4; ++k) { v[2 * k] = bf_lo(a[k]); v[2 * k + 1] = bf_hi(a[k]); v[8 + 2 * k] = bf_lo(c[k]); v[8 + 2 * k + 1] = bf_hi(c[k]); }
;             float s = 0.f;
; #pragma unroll
;             for (int k = 0; k < 16; ++k) s += v[k];
;             const float mu = wave_sum(s) * (1.0f / 1024.0f); float q = 0.f;
; #pragma unroll
;             for (int k = 0; k < 16; ++k) { const float d = v[k] - mu; q += d * d; }
;             mean[i] = mu; rstd[i] = 1.0f / sqrtf(wave_sum(q) * (1.0f / 1024.0f) + EPS); }
	v_add_f32_e32 v11, v11, v12
	v_mov_b32_e32 v12, v11
	s_nop 1
	v_permlane32_swap_b32_e32 v11, v12
	v_add_f32_e32 v11, v11, v12
	v_fmamk_f32 v11, v11, 0x3a800000, v244
	v_cmp_gt_f32_e32 vcc, s81, v11
	v_mul_f32_e32 v12, 0x4f800000, v11
	s_nop 0
	v_cndmask_b32_e32 v11, v11, v12, vcc
	v_sqrt_f32_e32 v12, v11
	s_nop 0
	v_add_u32_e32 v13, -1, v12
	v_fma_f32 v14, -v13, v12, v11
	v_cmp_ge_f32_e64 s[4:5], 0, v14
	v_add_u32_e32 v14, 1, v12
	s_nop 0
	v_cndmask_b32_e64 v13, v12, v13, s[4:5]
	v_fma_f32 v12, -v14, v12, v11
	v_cmp_lt_f32_e64 s[4:5], 0, v12
	s_nop 1
	v_cndmask_b32_e64 v12, v13, v14, s[4:5]
	v_mul_f32_e32 v13, 0x37800000, v12
	v_cndmask_b32_e32 v12, v12, v13, vcc
	v_cmp_class_f32_e32 vcc, v11, v245
	s_nop 1
	v_cndmask_b32_e32 v11, v12, v11, vcc
	v_div_scale_f32 v12, s[4:5], v11, v11, 1.0
	v_rcp_f32_e32 v13, v12
	s_or_b32 s4, s22, 5
	s_ashr_i32 s5, s4, 31
	s_lshl_b64 s[26:27], s[4:5], 11
	v_fma_f32 v14, -v12, v13, 1.0
	v_fmac_f32_e32 v13, v14, v13
	v_div_scale_f32 v14, vcc, 1.0, v11, 1.0
	v_mul_f32_e32 v15, v14, v13
	v_fma_f32 v17, -v12, v15, v14
	v_fmac_f32_e32 v15, v17, v13
	v_fma_f32 v12, -v12, v15, v14
	s_add_u32 s4, s6, s26
	v_div_fmas_f32 v12, v12, v13, v15
	s_addc_u32 s5, s7, s27
	v_div_fixup_f32 v11, v12, v11, 1.0
	s_waitcnt vmcnt(20)
	v_mov_b32_e32 v12, v104
	v_mov_b32_e32 v13, v105
	v_mov_b32_e32 v14, v106
	v_mov_b32_e32 v15, v107
	v_mov_b32_e32 v18, v108
	v_mov_b32_e32 v19, v109
	v_mov_b32_e32 v20, v110
	v_mov_b32_e32 v21, v111
	v_lshlrev_b32_e32 v17, 16, v12
	v_and_b32_e32 v22, 0xffff0000, v12
	v_add_f32_e32 v12, 0, v17
	v_lshlrev_b32_e32 v24, 16, v13
	v_add_f32_e32 v12, v12, v22
	v_and_b32_e32 v13, 0xffff0000, v13
	v_add_f32_e32 v12, v12, v24
	v_lshlrev_b32_e32 v26, 16, v14
	v_add_f32_e32 v12, v12, v13
	v_and_b32_e32 v14, 0xffff0000, v14
	v_add_f32_e32 v12, v12, v26
	v_lshlrev_b32_e32 v28, 16, v15
	v_add_f32_e32 v12, v12, v14
	v_and_b32_e32 v15, 0xffff0000, v15
	v_add_f32_e32 v12, v12, v28
	v_lshlrev_b32_e32 v23, 16, v18
	v_add_f32_e32 v12, v12, v15
	v_and_b32_e32 v18, 0xffff0000, v18
	v_add_f32_e32 v12, v12, v23
	v_lshlrev_b32_e32 v25, 16, v19
	v_add_f32_e32 v12, v12, v18
	v_and_b32_e32 v19, 0xffff0000, v19
	v_add_f32_e32 v12, v12, v25
	v_lshlrev_b32_e32 v27, 16, v20
	v_add_f32_e32 v12, v12, v19
	v_and_b32_e32 v20, 0xffff0000, v20
	v_add_f32_e32 v12, v12, v27
	v_lshlrev_b32_e32 v29, 16, v21
	v_add_f32_e32 v12, v12, v20
	v_and_b32_e32 v21, 0xffff0000, v21
	v_add_f32_e32 v12, v12, v29
	v_add_f32_e32 v12, v12, v21
	s_nop 1
	v_add_f32_dpp v12, v12, v12 quad_perm:[1,0,3,2] row_mask:0xf bank_mask:0xf bound_ctrl:1
	s_nop 1
	v_add_f32_dpp v12, v12, v12 quad_perm:[2,3,0,1] row_mask:0xf bank_mask:0xf bound_ctrl:1
	s_nop 1
	v_add_f32_dpp v12, v12, v12 row_half_mirror row_mask:0xf bank_mask:0xf bound_ctrl:1
	s_nop 1
	v_add_f32_dpp v12, v12, v12 row_mirror row_mask:0xf bank_mask:0xf bound_ctrl:1
	ds_swizzle_b32 v30, v12 offset:swizzle(SWAP,16)
	s_waitcnt lgkmcnt(0)
	v_add_f32_e32 v12, v12, v30
	v_mov_b32_e32 v30, v12
	s_nop 1
	v_permlane32_swap_b32_e32 v12, v30
	v_add_f32_e32 v12, v12, v30
	v_fmac_f32_e32 v22, 0xba800000, v12
	v_fmac_f32_e32 v17, 0xba800000, v12
	v_mul_f32_e32 v22, v22, v22
	v_fmac_f32_e32 v22, v17, v17
	v_fmac_f32_e32 v24, 0xba800000, v12
	v_fmac_f32_e32 v22, v24, v24
	v_fmac_f32_e32 v13, 0xba800000, v12
	v_fmac_f32_e32 v22, v13, v13
	v_fmac_f32_e32 v26, 0xba800000, v12
	v_fmac_f32_e32 v22, v26, v26
	v_fmac_f32_e32 v14, 0xba800000, v12
	v_fmac_f32_e32 v22, v14, v14
	v_fmac_f32_e32 v28, 0xba800000, v12
	v_fmac_f32_e32 v22, v28, v28
	v_fmac_f32_e32 v15, 0xba800000, v12
	v_fmac_f32_e32 v22, v15, v15
	v_fmac_f32_e32 v23, 0xba800000, v12
	v_fmac_f32_e32 v22, v23, v23
	v_fmac_f32_e32 v18, 0xba800000, v12
	v_fmac_f32_e32 v22, v18, v18
	v_fmac_f32_e32 v25, 0xba800000, v12
	v_fmac_f32_e32 v22, v25, v25
	v_fmac_f32_e32 v19, 0xba800000, v12
	v_fmac_f32_e32 v22, v19, v19
	v_fmac_f32_e32 v27, 0xba800000, v12
	v_fmac_f32_e32 v22, v27, v27
	v_fmac_f32_e32 v20, 0xba800000, v12
	v_fmac_f32_e32 v22, v20, v20
	v_fmac_f32_e32 v29, 0xba800000, v12
	v_fmac_f32_e32 v22, v29, v29
	v_fmac_f32_e32 v21, 0xba800000, v12
	v_fmac_f32_e32 v22, v21, v21
	s_nop 1
	v_add_f32_dpp v13, v22, v22 quad_perm:[1,0,3,2] row_mask:0xf bank_mask:0xf bound_ctrl:1
	s_nop 1
	v_add_f32_dpp v13, v13, v13 quad_perm:[2,3,0,1] row_mask:0xf bank_mask:0xf bound_ctrl:1
	s_nop 1
	v_add_f32_dpp v13, v13, v13 row_half_mirror row_mask:0xf bank_mask:0xf bound_ctrl:1
	s_nop 1
	v_add_f32_dpp v13, v13, v13 row_mirror row_mask:0xf bank_mask:0xf bound_ctrl:1
	ds_swizzle_b32 v14, v13 offset:swizzle(SWAP,16)
	s_waitcnt lgkmcnt(0)
	v_add_f32_e32 v13, v13, v14
	v_mov_b32_e32 v14, v13
	s_nop 1
	v_permlane32_swap_b32_e32 v13, v14
	v_add_f32_e32 v13, v13, v14
	v_fmamk_f32 v13, v13, 0x3a800000, v244
	v_cmp_gt_f32_e32 vcc, s81, v13
	v_mul_f32_e32 v14, 0x4f800000, v13
	s_nop 0
	v_cndmask_b32_e32 v13, v13, v14, vcc
	v_sqrt_f32_e32 v14, v13
	s_nop 0
	v_add_u32_e32 v15, -1, v14
	v_fma_f32 v17, -v15, v14, v13
	v_cmp_ge_f32_e64 s[4:5], 0, v17
	v_add_u32_e32 v17, 1, v14
	s_nop 0
	v_cndmask_b32_e64 v15, v14, v15, s[4:5]
	v_fma_f32 v14, -v17, v14, v13
	v_cmp_lt_f32_e64 s[4:5], 0, v14
	s_nop 1
	v_cndmask_b32_e64 v14, v15, v17, s[4:5]
	v_mul_f32_e32 v15, 0x37800000, v14
	v_cndmask_b32_e32 v14, v14, v15, vcc
	v_cmp_class_f32_e32 vcc, v13, v245
	s_nop 1
	v_cndmask_b32_e32 v13, v14, v13, vcc
	v_div_scale_f32 v14, s[4:5], v13, v13, 1.0
	v_rcp_f32_e32 v15, v14
	s_or_b32 s4, s22, 6
	s_ashr_i32 s5, s4, 31
	s_lshl_b64 s[36:37], s[4:5], 11
	v_fma_f32 v17, -v14, v15, 1.0
	v_fmac_f32_e32 v15, v17, v15
	v_div_scale_f32 v17, vcc, 1.0, v13, 1.0
	v_mul_f32_e32 v18, v17, v15
	v_fma_f32 v19, -v14, v18, v17
	v_fmac_f32_e32 v18, v19, v15
	s_add_u32 s4, s6, s36
	v_fma_f32 v14, -v14, v18, v17
	s_addc_u32 s5, s7, s37
	v_div_fmas_f32 v14, v14, v15, v18
	s_waitcnt vmcnt(18)
; __device__ __forceinline__ float bf_lo(unsigned v) { return __uint_as_float(v << 16); }
; __device__ __forceinline__ float bf_hi(unsigned v) { return __uint_as_float(v & 0xffff0000u); }
; __device__ __forceinline__ void sgu_item(int it, const bf16_t* GV, const bf16_t* ZU, const float* sg_, const float* sb_, const float* wsp, const float* bsp, bf16_t* CAT, unsigned char* lds, const int wv) {
;     ...
;         for (int i = 0; i < 16; ++i) { const bf16_t* row = GV + (size_t)(tok0 + 16 * wid + i) * 1024;
;             const u32x4 a = *(const u32x4*)(row + 8 * lane), c = *(const u32x4*)(row + 512 + 8 * lane);
;             float v[16];
; #pragma unroll
;             for (int k = 0; k < 4; ++k) { v[2 * k] = bf_lo(a[k]); v[2 * k + 1] = bf_hi(a[k]); v[8 + 2 * k] = bf_lo(c[k]); v[8 + 2 * k + 1] = bf_hi(c[k]); }
;             float s = 0.f;
; #pragma unroll
;             for (int k = 0; k < 16; ++k) s += v[k];
;             const float mu = wave_sum(s) * (1.0f / 1024.0f); float q = 0.f;
; #pragma unroll
;             for (int k = 0; k < 16; ++k) { const float d = v[k] - mu; q += d * d; }
;             mean[i] = mu; rstd[i] = 1.0f / sqrtf(wave_sum(q) * (1.0f / 1024.0f) + EPS); }
	v_mov_b32_e32 v18, v112
	v_mov_b32_e32 v19, v113
	v_mov_b32_e32 v20, v114
	v_mov_b32_e32 v21, v115
	v_mov_b32_e32 v22, v116
	v_mov_b32_e32 v23, v117
	v_mov_b32_e32 v24, v118
	v_mov_b32_e32 v25, v119
	v_div_fixup_f32 v13, v14, v13, 1.0
	v_lshlrev_b32_e32 v15, 16, v18
	v_and_b32_e32 v17, 0xffff0000, v18
	v_add_f32_e32 v14, 0, v15
	v_lshlrev_b32_e32 v26, 16, v19
	v_add_f32_e32 v14, v14, v17
	v_and_b32_e32 v19, 0xffff0000, v19
	v_add_f32_e32 v14, v14, v26
	v_lshlrev_b32_e32 v28, 16, v20
	v_add_f32_e32 v14, v14, v19
	v_and_b32_e32 v20, 0xffff0000, v20
	v_add_f32_e32 v14, v14, v28
	v_lshlrev_b32_e32 v30, 16, v21
	v_add_f32_e32 v14, v14, v20
	v_and_b32_e32 v21, 0xffff0000, v21
	v_add_f32_e32 v14, v14, v30
	v_lshlrev_b32_e32 v18, 16, v22
	v_add_f32_e32 v14, v14, v21
	v_and_b32_e32 v22, 0xffff0000, v22
	v_add_f32_e32 v14, v14, v18
	v_lshlrev_b32_e32 v27, 16, v23
	v_add_f32_e32 v14, v14, v22
	v_and_b32_e32 v23, 0xffff0000, v23
	v_add_f32_e32 v14, v14, v27
	v_lshlrev_b32_e32 v29, 16, v24
	v_add_f32_e32 v14, v14, v23
	v_and_b32_e32 v24, 0xffff0000, v24
	v_add_f32_e32 v14, v14, v29
	v_lshlrev_b32_e32 v31, 16, v25
	v_add_f32_e32 v14, v14, v24
	v_and_b32_e32 v25, 0xffff0000, v25
	v_add_f32_e32 v14, v14, v31
	v_add_f32_e32 v14, v14, v25
	s_nop 1
	v_add_f32_dpp v14, v14, v14 quad_perm:[1,0,3,2] row_mask:0xf bank_mask:0xf bound_ctrl:1
	s_nop 1
	v_add_f32_dpp v14, v14, v14 quad_perm:[2,3,0,1] row_mask:0xf bank_mask:0xf bound_ctrl:1
	s_nop 1
	v_add_f32_dpp v14, v14, v14 row_half_mirror row_mask:0xf bank_mask:0xf bound_ctrl:1
	s_nop 1
	v_add_f32_dpp v14, v14, v14 row_mirror row_mask:0xf bank_mask:0xf bound_ctrl:1
	ds_swizzle_b32 v32, v14 offset:swizzle(SWAP,16)
	s_waitcnt lgkmcnt(0)
	v_add_f32_e32 v14, v14, v32
	v_mov_b32_e32 v32, v14
	s_nop 1
	v_permlane32_swap_b32_e32 v14, v32
	v_add_f32_e32 v14, v14, v32
	v_fmac_f32_e32 v17, 0xba800000, v14
	v_fmac_f32_e32 v15, 0xba800000, v14
	v_mul_f32_e32 v17, v17, v17
	v_fmac_f32_e32 v17, v15, v15
	v_fmac_f32_e32 v26, 0xba800000, v14
	v_fmac_f32_e32 v17, v26, v26
	v_fmac_f32_e32 v19, 0xba800000, v14
	v_fmac_f32_e32 v17, v19, v19
	v_fmac_f32_e32 v28, 0xba800000, v14
	v_fmac_f32_e32 v17, v28, v28
	v_fmac_f32_e32 v20, 0xba800000, v14
	v_fmac_f32_e32 v17, v20, v20
	v_fmac_f32_e32 v30, 0xba800000, v14
	v_fmac_f32_e32 v17, v30, v30
	v_fmac_f32_e32 v21, 0xba800000, v14
	v_fmac_f32_e32 v17, v21, v21
	v_fmac_f32_e32 v18, 0xba800000, v14
	v_fmac_f32_e32 v17, v18, v18
	v_fmac_f32_e32 v22, 0xba800000, v14
	v_fmac_f32_e32 v17, v22, v22
	v_fmac_f32_e32 v27, 0xba800000, v14
	v_fmac_f32_e32 v17, v27, v27
	v_fmac_f32_e32 v23, 0xba800000, v14
	v_fmac_f32_e32 v17, v23, v23
	v_fmac_f32_e32 v29, 0xba800000, v14
	v_fmac_f32_e32 v17, v29, v29
	v_fmac_f32_e32 v24, 0xba800000, v14
	v_fmac_f32_e32 v17, v24, v24
	v_fmac_f32_e32 v31, 0xba800000, v14
	v_fmac_f32_e32 v17, v31, v31
	v_fmac_f32_e32 v25, 0xba800000, v14
	v_fmac_f32_e32 v17, v25, v25
	s_nop 1
	v_add_f32_dpp v15, v17, v17 quad_perm:[1,0,3,2] row_mask:0xf bank_mask:0xf bound_ctrl:1
	s_nop 1
	v_add_f32_dpp v15, v15, v15 quad_perm:[2,3,0,1] row_mask:0xf bank_mask:0xf bound_ctrl:1
	s_nop 1
	v_add_f32_dpp v15, v15, v15 row_half_mirror row_mask:0xf bank_mask:0xf bound_ctrl:1
	s_nop 1
	v_add_f32_dpp v15, v15, v15 row_mirror row_mask:0xf bank_mask:0xf bound_ctrl:1
	ds_swizzle_b32 v17, v15 offset:swizzle(SWAP,16)
	s_waitcnt lgkmcnt(0)
	v_add_f32_e32 v15, v15, v17
	v_mov_b32_e32 v17, v15
	s_nop 1
	v_permlane32_swap_b32_e32 v15, v17
	v_add_f32_e32 v15, v15, v17
	v_fmamk_f32 v15, v15, 0x3a800000, v244
	v_cmp_gt_f32_e32 vcc, s81, v15
	v_mul_f32_e32 v17, 0x4f800000, v15
	s_nop 0
	v_cndmask_b32_e32 v15, v15, v17, vcc
	v_sqrt_f32_e32 v17, v15
	s_nop 0
	v_add_u32_e32 v18, -1, v17
	v_fma_f32 v19, -v18, v17, v15
	v_cmp_ge_f32_e64 s[4:5], 0, v19
	v_add_u32_e32 v19, 1, v17
	s_nop 0
	v_cndmask_b32_e64 v18, v17, v18, s[4:5]
	v_fma_f32 v17, -v19, v17, v15
	v_cmp_lt_f32_e64 s[4:5], 0, v17
	s_nop 1
	v_cndmask_b32_e64 v17, v18, v19, s[4:5]
	v_mul_f32_e32 v18, 0x37800000, v17
	v_cndmask_b32_e32 v17, v17, v18, vcc
	v_cmp_class_f32_e32 vcc, v15, v245
	s_nop 1
	v_cndmask_b32_e32 v15, v17, v15, vcc
	v_div_scale_f32 v17, s[4:5], v15, v15, 1.0
	v_rcp_f32_e32 v18, v17
	s_or_b32 s4, s22, 7
	s_ashr_i32 s5, s4, 31
	s_lshl_b64 s[42:43], s[4:5], 11
	v_fma_f32 v19, -v17, v18, 1.0
	v_fmac_f32_e32 v18, v19, v18
	v_div_scale_f32 v19, vcc, 1.0, v15, 1.0
	v_mul_f32_e32 v20, v19, v18
	v_fma_f32 v21, -v17, v20, v19
	v_fmac_f32_e32 v20, v21, v18
	s_add_u32 s4, s6, s42
	v_fma_f32 v17, -v17, v20, v19
	s_addc_u32 s5, s7, s43
	v_div_fmas_f32 v17, v17, v18, v20
	s_waitcnt vmcnt(16)
	v_mov_b32_e32 v18, v120
	v_mov_b32_e32 v19, v121
	v_mov_b32_e32 v20, v122
	v_mov_b32_e32 v21, v123
	v_mov_b32_e32 v22, v124
	v_mov_b32_e32 v23, v125
	v_mov_b32_e32 v24, v126
	v_mov_b32_e32 v25, v127
	v_div_fixup_f32 v15, v17, v15, 1.0
	v_lshlrev_b32_e32 v26, 16, v18
	v_and_b32_e32 v18, 0xffff0000, v18
	v_add_f32_e32 v17, 0, v26
	v_lshlrev_b32_e32 v28, 16, v19
	v_add_f32_e32 v17, v17, v18
	v_and_b32_e32 v19, 0xffff0000, v19
	v_add_f32_e32 v17, v17, v28
	v_lshlrev_b32_e32 v30, 16, v20
	v_add_f32_e32 v17, v17, v19
	v_and_b32_e32 v20, 0xffff0000, v20
	v_add_f32_e32 v17, v17, v30
	v_lshlrev_b32_e32 v32, 16, v21
	v_add_f32_e32 v17, v17, v20
	v_and_b32_e32 v21, 0xffff0000, v21
	v_add_f32_e32 v17, v17, v32
	v_lshlrev_b32_e32 v27, 16, v22
	v_add_f32_e32 v17, v17, v21
	v_and_b32_e32 v22, 0xffff0000, v22
	v_add_f32_e32 v17, v17, v27
	v_lshlrev_b32_e32 v29, 16, v23
	v_add_f32_e32 v17, v17, v22
	v_and_b32_e32 v23, 0xffff0000, v23
	v_add_f32_e32 v17, v17, v29
	v_lshlrev_b32_e32 v31, 16, v24
	v_add_f32_e32 v17, v17, v23
	v_and_b32_e32 v24, 0xffff0000, v24
	v_add_f32_e32 v17, v17, v31
	v_lshlrev_b32_e32 v33, 16, v25
	v_add_f32_e32 v17, v17, v24
	v_and_b32_e32 v25, 0xffff0000, v25
	v_add_f32_e32 v17, v17, v33
	v_add_f32_e32 v17, v17, v25
	s_nop 1
	v_add_f32_dpp v17, v17, v17 quad_perm:[1,0,3,2] row_mask:0xf bank_mask:0xf bound_ctrl:1
	s_nop 1
	v_add_f32_dpp v17, v17, v17 quad_perm:[2,3,0,1] row_mask:0xf bank_mask:0xf bound_ctrl:1
	s_nop 1
	v_add_f32_dpp v17, v17, v17 row_half_mirror row_mask:0xf bank_mask:0xf bound_ctrl:1
	s_nop 1
	v_add_f32_dpp v17, v17, v17 row_mirror row_mask:0xf bank_mask:0xf bound_ctrl:1
	ds_swizzle_b32 v34, v17 offset:swizzle(SWAP,16)
	s_waitcnt lgkmcnt(0)
; __device__ __forceinline__ float bf_lo(unsigned v) { return __uint_as_float(v << 16); }
; __device__ __forceinline__ float bf_hi(unsigned v) { return __uint_as_float(v & 0xffff0000u); }
; __device__ __forceinline__ void sgu_item(int it, const bf16_t* GV, const bf16_t* ZU, const float* sg_, const float* sb_, const float* wsp, const float* bsp, bf16_t* CAT, unsigned char* lds, const int wv) {
;     ...
;         for (int i = 0; i < 16; ++i) { const bf16_t* row = GV + (size_t)(tok0 + 16 * wid + i) * 1024;
;             const u32x4 a = *(const u32x4*)(row + 8 * lane), c = *(const u32x4*)(row + 512 + 8 * lane);
;             float v[16];
; #pragma unroll
;             for (int k = 0; k < 4; ++k) { v[2 * k] = bf_lo(a[k]); v[2 * k + 1] = bf_hi(a[k]); v[8 + 2 * k] = bf_lo(c[k]); v[8 + 2 * k + 1] = bf_hi(c[k]); }
;             float s = 0.f;
; #pragma unroll
;             for (int k = 0; k < 16; ++k) s += v[k];
;             const float mu = wave_sum(s) * (1.0f / 1024.0f); float q = 0.f;
; #pragma unroll
;             for (int k = 0; k < 16; ++k) { const float d = v[k] - mu; q += d * d; }
;             mean[i] = mu; rstd[i] = 1.0f / sqrtf(wave_sum(q) * (1.0f / 1024.0f) + EPS); }
	v_add_f32_e32 v17, v17, v34
	v_mov_b32_e32 v34, v17
	s_nop 1
	v_permlane32_swap_b32_e32 v17, v34
	v_add_f32_e32 v17, v17, v34
	v_fmac_f32_e32 v18, 0xba800000, v17
	v_fmac_f32_e32 v26, 0xba800000, v17
	v_mul_f32_e32 v18, v18, v18
	v_fmac_f32_e32 v18, v26, v26
	v_fmac_f32_e32 v28, 0xba800000, v17
	v_fmac_f32_e32 v18, v28, v28
	v_fmac_f32_e32 v19, 0xba800000, v17
	v_fmac_f32_e32 v18, v19, v19
	v_fmac_f32_e32 v30, 0xba800000, v17
	v_fmac_f32_e32 v18, v30, v30
	v_fmac_f32_e32 v20, 0xba800000, v17
	v_fmac_f32_e32 v18, v20, v20
	v_fmac_f32_e32 v32, 0xba800000, v17
	v_fmac_f32_e32 v18, v32, v32
	v_fmac_f32_e32 v21, 0xba800000, v17
	v_fmac_f32_e32 v18, v21, v21
	v_fmac_f32_e32 v27, 0xba800000, v17
	v_fmac_f32_e32 v18, v27, v27
	v_fmac_f32_e32 v22, 0xba800000, v17
	v_fmac_f32_e32 v18, v22, v22
	v_fmac_f32_e32 v29, 0xba800000, v17
	v_fmac_f32_e32 v18, v29, v29
	v_fmac_f32_e32 v23, 0xba800000, v17
	v_fmac_f32_e32 v18, v23, v23
	v_fmac_f32_e32 v31, 0xba800000, v17
	v_fmac_f32_e32 v18, v31, v31
	v_fmac_f32_e32 v24, 0xba800000, v17
	v_fmac_f32_e32 v18, v24, v24
	v_fmac_f32_e32 v33, 0xba800000, v17
	v_fmac_f32_e32 v18, v33, v33
	v_fmac_f32_e32 v25, 0xba800000, v17
	v_fmac_f32_e32 v18, v25, v25
	s_nop 1
	v_add_f32_dpp v18, v18, v18 quad_perm:[1,0,3,2] row_mask:0xf bank_mask:0xf bound_ctrl:1
	s_nop 1
	v_add_f32_dpp v18, v18, v18 quad_perm:[2,3,0,1] row_mask:0xf bank_mask:0xf bound_ctrl:1
	s_nop 1
	v_add_f32_dpp v18, v18, v18 row_half_mirror row_mask:0xf bank_mask:0xf bound_ctrl:1
	s_nop 1
	v_add_f32_dpp v18, v18, v18 row_mirror row_mask:0xf bank_mask:0xf bound_ctrl:1
	ds_swizzle_b32 v19, v18 offset:swizzle(SWAP,16)
	s_waitcnt lgkmcnt(0)
	v_add_f32_e32 v18, v18, v19
	v_mov_b32_e32 v19, v18
	s_nop 1
	v_permlane32_swap_b32_e32 v18, v19
	v_add_f32_e32 v18, v18, v19
	v_fmamk_f32 v18, v18, 0x3a800000, v244
	v_cmp_gt_f32_e32 vcc, s81, v18
	v_mul_f32_e32 v19, 0x4f800000, v18
	s_nop 0
	v_cndmask_b32_e32 v18, v18, v19, vcc
	v_sqrt_f32_e32 v19, v18
	s_nop 0
	v_add_u32_e32 v20, -1, v19
	v_fma_f32 v21, -v20, v19, v18
	v_cmp_ge_f32_e64 s[4:5], 0, v21
	v_add_u32_e32 v21, 1, v19
	s_nop 0
	v_cndmask_b32_e64 v20, v19, v20, s[4:5]
	v_fma_f32 v19, -v21, v19, v18
	v_cmp_lt_f32_e64 s[4:5], 0, v19
	s_nop 1
	v_cndmask_b32_e64 v19, v20, v21, s[4:5]
	v_mul_f32_e32 v20, 0x37800000, v19
	v_cndmask_b32_e32 v19, v19, v20, vcc
	v_cmp_class_f32_e32 vcc, v18, v245
	s_nop 1
	v_cndmask_b32_e32 v18, v19, v18, vcc
	v_div_scale_f32 v19, s[4:5], v18, v18, 1.0
	v_rcp_f32_e32 v20, v19
	s_or_b32 s4, s22, 8
	s_ashr_i32 s5, s4, 31
	s_lshl_b64 s[44:45], s[4:5], 11
	v_fma_f32 v21, -v19, v20, 1.0
	v_fmac_f32_e32 v20, v21, v20
	v_div_scale_f32 v21, vcc, 1.0, v18, 1.0
	v_mul_f32_e32 v22, v21, v20
	v_fma_f32 v23, -v19, v22, v21
	v_fmac_f32_e32 v22, v23, v20
	s_add_u32 s4, s6, s44
	v_fma_f32 v19, -v19, v22, v21
	s_addc_u32 s5, s7, s45
	v_div_fmas_f32 v19, v19, v20, v22
	s_waitcnt vmcnt(14)
	v_mov_b32_e32 v20, v128
	v_mov_b32_e32 v21, v129
	v_mov_b32_e32 v22, v130
	v_mov_b32_e32 v23, v131
	v_mov_b32_e32 v24, v132
	v_mov_b32_e32 v25, v133
	v_mov_b32_e32 v26, v134
	v_mov_b32_e32 v27, v135
	v_div_fixup_f32 v18, v19, v18, 1.0
	v_lshlrev_b32_e32 v28, 16, v20
	v_and_b32_e32 v20, 0xffff0000, v20
	v_add_f32_e32 v19, 0, v28
	v_lshlrev_b32_e32 v30, 16, v21
	v_add_f32_e32 v19, v19, v20
	v_and_b32_e32 v21, 0xffff0000, v21
	v_add_f32_e32 v19, v19, v30
	v_lshlrev_b32_e32 v32, 16, v22
	v_add_f32_e32 v19, v19, v21
	v_and_b32_e32 v22, 0xffff0000, v22
	v_add_f32_e32 v19, v19, v32
	v_lshlrev_b32_e32 v34, 16, v23
	v_add_f32_e32 v19, v19, v22
	v_and_b32_e32 v23, 0xffff0000, v23
	v_add_f32_e32 v19, v19, v34
	v_lshlrev_b32_e32 v29, 16, v24
	v_add_f32_e32 v19, v19, v23
	v_and_b32_e32 v24, 0xffff0000, v24
	v_add_f32_e32 v19, v19, v29
	v_lshlrev_b32_e32 v31, 16, v25
	v_add_f32_e32 v19, v19, v24
	v_and_b32_e32 v25, 0xffff0000, v25
	v_add_f32_e32 v19, v19, v31
	v_lshlrev_b32_e32 v33, 16, v26
	v_add_f32_e32 v19, v19, v25
	v_and_b32_e32 v26, 0xffff0000, v26
	v_add_f32_e32 v19, v19, v33
	v_lshlrev_b32_e32 v35, 16, v27
	v_add_f32_e32 v19, v19, v26
	v_and_b32_e32 v27, 0xffff0000, v27
	v_add_f32_e32 v19, v19, v35
	v_add_f32_e32 v19, v19, v27
	s_nop 1
	v_add_f32_dpp v19, v19, v19 quad_perm:[1,0,3,2] row_mask:0xf bank_mask:0xf bound_ctrl:1
	s_nop 1
	v_add_f32_dpp v19, v19, v19 quad_perm:[2,3,0,1] row_mask:0xf bank_mask:0xf bound_ctrl:1
	s_nop 1
	v_add_f32_dpp v19, v19, v19 row_half_mirror row_mask:0xf bank_mask:0xf bound_ctrl:1
	s_nop 1
	v_add_f32_dpp v19, v19, v19 row_mirror row_mask:0xf bank_mask:0xf bound_ctrl:1
	ds_swizzle_b32 v36, v19 offset:swizzle(SWAP,16)
	s_waitcnt lgkmcnt(0)
	v_add_f32_e32 v19, v19, v36
	v_mov_b32_e32 v36, v19
	s_nop 1
	v_permlane32_swap_b32_e32 v19, v36
	v_add_f32_e32 v19, v19, v36
	v_fmac_f32_e32 v20, 0xba800000, v19
	v_fmac_f32_e32 v28, 0xba800000, v19
	v_mul_f32_e32 v20, v20, v20
	v_fmac_f32_e32 v20, v28, v28
	v_fmac_f32_e32 v30, 0xba800000, v19
	v_fmac_f32_e32 v20, v30, v30
	v_fmac_f32_e32 v21, 0xba800000, v19
	v_fmac_f32_e32 v20, v21, v21
	v_fmac_f32_e32 v32, 0xba800000, v19
	v_fmac_f32_e32 v20, v32, v32
	v_fmac_f32_e32 v22, 0xba800000, v19
	v_fmac_f32_e32 v20, v22, v22
	v_fmac_f32_e32 v34, 0xba800000, v19
	v_fmac_f32_e32 v20, v34, v34
	v_fmac_f32_e32 v23, 0xba800000, v19
	v_fmac_f32_e32 v20, v23, v23
	v_fmac_f32_e32 v29, 0xba800000, v19
	v_fmac_f32_e32 v20, v29, v29
	v_fmac_f32_e32 v24, 0xba800000, v19
	v_fmac_f32_e32 v20, v24, v24
	v_fmac_f32_e32 v31, 0xba800000, v19
	v_fmac_f32_e32 v20, v31, v31
	v_fmac_f32_e32 v25, 0xba800000, v19
	v_fmac_f32_e32 v20, v25, v25
	v_fmac_f32_e32 v33, 0xba800000, v19
	v_fmac_f32_e32 v20, v33, v33
	v_fmac_f32_e32 v26, 0xba800000, v19
	v_fmac_f32_e32 v20, v26, v26
	v_fmac_f32_e32 v35, 0xba800000, v19
	v_fmac_f32_e32 v20, v35, v35
	v_fmac_f32_e32 v27, 0xba800000, v19
	v_fmac_f32_e32 v20, v27, v27
	s_nop 1
	v_add_f32_dpp v20, v20, v20 quad_perm:[1,0,3,2] row_mask:0xf bank_mask:0xf bound_ctrl:1
	s_nop 1
	v_add_f32_dpp v20, v20, v20 quad_perm:[2,3,0,1] row_mask:0xf bank_mask:0xf bound_ctrl:1
	s_nop 1
	v_add_f32_dpp v20, v20, v20 row_half_mirror row_mask:0xf bank_mask:0xf bound_ctrl:1
	s_nop 1
	v_add_f32_dpp v20, v20, v20 row_mirror row_mask:0xf bank_mask:0xf bound_ctrl:1
	ds_swizzle_b32 v21, v20 offset:swizzle(SWAP,16)
	s_waitcnt lgkmcnt(0)
; __device__ __forceinline__ float bf_lo(unsigned v) { return __uint_as_float(v << 16); }
; __device__ __forceinline__ float bf_hi(unsigned v) { return __uint_as_float(v & 0xffff0000u); }
; __device__ __forceinline__ void sgu_item(int it, const bf16_t* GV, const bf16_t* ZU, const float* sg_, const float* sb_, const float* wsp, const float* bsp, bf16_t* CAT, unsigned char* lds, const int wv) {
;     ...
;         for (int i = 0; i < 16; ++i) { const bf16_t* row = GV + (size_t)(tok0 + 16 * wid + i) * 1024;
;             const u32x4 a = *(const u32x4*)(row + 8 * lane), c = *(const u32x4*)(row + 512 + 8 * lane);
;             float v[16];
; #pragma unroll
;             for (int k = 0; k < 4; ++k) { v[2 * k] = bf_lo(a[k]); v[2 * k + 1] = bf_hi(a[k]); v[8 + 2 * k] = bf_lo(c[k]); v[8 + 2 * k + 1] = bf_hi(c[k]); }
;             float s = 0.f;
; #pragma unroll
;             for (int k = 0; k < 16; ++k) s += v[k];
;             const float mu = wave_sum(s) * (1.0f / 1024.0f); float q = 0.f;
; #pragma unroll
;             for (int k = 0; k < 16; ++k) { const float d = v[k] - mu; q += d * d; }
;             mean[i] = mu; rstd[i] = 1.0f / sqrtf(wave_sum(q) * (1.0f / 1024.0f) + EPS); }
	v_add_f32_e32 v20, v20, v21
	v_mov_b32_e32 v21, v20
	s_nop 1
	v_permlane32_swap_b32_e32 v20, v21
	v_add_f32_e32 v20, v20, v21
	v_fmamk_f32 v20, v20, 0x3a800000, v244
	v_cmp_gt_f32_e32 vcc, s81, v20
	v_mul_f32_e32 v21, 0x4f800000, v20
	s_nop 0
	v_cndmask_b32_e32 v20, v20, v21, vcc
	v_sqrt_f32_e32 v21, v20
	s_nop 0
	v_add_u32_e32 v22, -1, v21
	v_fma_f32 v23, -v22, v21, v20
	v_cmp_ge_f32_e64 s[4:5], 0, v23
	v_add_u32_e32 v23, 1, v21
	s_nop 0
	v_cndmask_b32_e64 v22, v21, v22, s[4:5]
	v_fma_f32 v21, -v23, v21, v20
	v_cmp_lt_f32_e64 s[4:5], 0, v21
	s_nop 1
	v_cndmask_b32_e64 v21, v22, v23, s[4:5]
	v_mul_f32_e32 v22, 0x37800000, v21
	v_cndmask_b32_e32 v21, v21, v22, vcc
	v_cmp_class_f32_e32 vcc, v20, v245
	s_nop 1
	v_cndmask_b32_e32 v20, v21, v20, vcc
	v_div_scale_f32 v21, s[4:5], v20, v20, 1.0
	v_rcp_f32_e32 v22, v21
	s_or_b32 s4, s22, 9
	s_ashr_i32 s5, s4, 31
	s_lshl_b64 s[10:11], s[4:5], 11
	v_fma_f32 v23, -v21, v22, 1.0
	v_fmac_f32_e32 v22, v23, v22
	v_div_scale_f32 v23, vcc, 1.0, v20, 1.0
	v_mul_f32_e32 v24, v23, v22
	v_fma_f32 v25, -v21, v24, v23
	v_fmac_f32_e32 v24, v25, v22
	s_add_u32 s4, s6, s10
	v_fma_f32 v21, -v21, v24, v23
	s_addc_u32 s5, s7, s11
	v_div_fmas_f32 v21, v21, v22, v24
	s_waitcnt vmcnt(12)
	v_mov_b32_e32 v22, v136
	v_mov_b32_e32 v23, v137
	v_mov_b32_e32 v24, v138
	v_mov_b32_e32 v25, v139
	v_mov_b32_e32 v26, v140
	v_mov_b32_e32 v27, v141
	v_mov_b32_e32 v28, v142
	v_mov_b32_e32 v29, v143
	v_div_fixup_f32 v20, v21, v20, 1.0
	v_lshlrev_b32_e32 v30, 16, v22
	v_and_b32_e32 v22, 0xffff0000, v22
	v_add_f32_e32 v21, 0, v30
	v_lshlrev_b32_e32 v32, 16, v23
	v_add_f32_e32 v21, v21, v22
	v_and_b32_e32 v23, 0xffff0000, v23
	v_add_f32_e32 v21, v21, v32
	v_lshlrev_b32_e32 v34, 16, v24
	v_add_f32_e32 v21, v21, v23
	v_and_b32_e32 v24, 0xffff0000, v24
	v_add_f32_e32 v21, v21, v34
	v_lshlrev_b32_e32 v36, 16, v25
	v_add_f32_e32 v21, v21, v24
	v_and_b32_e32 v25, 0xffff0000, v25
	v_add_f32_e32 v21, v21, v36
	v_lshlrev_b32_e32 v31, 16, v26
	v_add_f32_e32 v21, v21, v25
	v_and_b32_e32 v26, 0xffff0000, v26
	v_add_f32_e32 v21, v21, v31
	v_lshlrev_b32_e32 v33, 16, v27
	v_add_f32_e32 v21, v21, v26
	v_and_b32_e32 v27, 0xffff0000, v27
	v_add_f32_e32 v21, v21, v33
	v_lshlrev_b32_e32 v35, 16, v28
	v_add_f32_e32 v21, v21, v27
	v_and_b32_e32 v28, 0xffff0000, v28
	v_add_f32_e32 v21, v21, v35
	v_lshlrev_b32_e32 v37, 16, v29
	v_add_f32_e32 v21, v21, v28
	v_and_b32_e32 v29, 0xffff0000, v29
	v_add_f32_e32 v21, v21, v37
	v_add_f32_e32 v21, v21, v29
	s_nop 1
	v_add_f32_dpp v21, v21, v21 quad_perm:[1,0,3,2] row_mask:0xf bank_mask:0xf bound_ctrl:1
	s_nop 1
	v_add_f32_dpp v21, v21, v21 quad_perm:[2,3,0,1] row_mask:0xf bank_mask:0xf bound_ctrl:1
	s_nop 1
	v_add_f32_dpp v21, v21, v21 row_half_mirror row_mask:0xf bank_mask:0xf bound_ctrl:1
	s_nop 1
	v_add_f32_dpp v21, v21, v21 row_mirror row_mask:0xf bank_mask:0xf bound_ctrl:1
	ds_swizzle_b32 v38, v21 offset:swizzle(SWAP,16)
	s_waitcnt lgkmcnt(0)
	v_add_f32_e32 v21, v21, v38
	v_mov_b32_e32 v38, v21
	s_nop 1
	v_permlane32_swap_b32_e32 v21, v38
	v_add_f32_e32 v21, v21, v38
	v_fmac_f32_e32 v22, 0xba800000, v21
	v_fmac_f32_e32 v30, 0xba800000, v21
	v_mul_f32_e32 v22, v22, v22
	v_fmac_f32_e32 v22, v30, v30
	v_fmac_f32_e32 v32, 0xba800000, v21
	v_fmac_f32_e32 v22, v32, v32
	v_fmac_f32_e32 v23, 0xba800000, v21
	v_fmac_f32_e32 v22, v23, v23
	v_fmac_f32_e32 v34, 0xba800000, v21
	v_fmac_f32_e32 v22, v34, v34
	v_fmac_f32_e32 v24, 0xba800000, v21
	v_fmac_f32_e32 v22, v24, v24
	v_fmac_f32_e32 v36, 0xba800000, v21
	v_fmac_f32_e32 v22, v36, v36
	v_fmac_f32_e32 v25, 0xba800000, v21
	v_fmac_f32_e32 v22, v25, v25
	v_fmac_f32_e32 v31, 0xba800000, v21
	v_fmac_f32_e32 v22, v31, v31
	v_fmac_f32_e32 v26, 0xba800000, v21
	v_fmac_f32_e32 v22, v26, v26
	v_fmac_f32_e32 v33, 0xba800000, v21
	v_fmac_f32_e32 v22, v33, v33
	v_fmac_f32_e32 v27, 0xba800000, v21
	v_fmac_f32_e32 v22, v27, v27
	v_fmac_f32_e32 v35, 0xba800000, v21
	v_fmac_f32_e32 v22, v35, v35
	v_fmac_f32_e32 v28, 0xba800000, v21
	v_fmac_f32_e32 v22, v28, v28
	v_fmac_f32_e32 v37, 0xba800000, v21
	v_fmac_f32_e32 v22, v37, v37
	v_fmac_f32_e32 v29, 0xba800000, v21
	v_fmac_f32_e32 v22, v29, v29
	s_nop 1
	v_add_f32_dpp v22, v22, v22 quad_perm:[1,0,3,2] row_mask:0xf bank_mask:0xf bound_ctrl:1
	s_nop 1
	v_add_f32_dpp v22, v22, v22 quad_perm:[2,3,0,1] row_mask:0xf bank_mask:0xf bound_ctrl:1
	s_nop 1
	v_add_f32_dpp v22, v22, v22 row_half_mirror row_mask:0xf bank_mask:0xf bound_ctrl:1
	s_nop 1
	v_add_f32_dpp v22, v22, v22 row_mirror row_mask:0xf bank_mask:0xf bound_ctrl:1
	ds_swizzle_b32 v23, v22 offset:swizzle(SWAP,16)
	s_waitcnt lgkmcnt(0)
	v_add_f32_e32 v22, v22, v23
	v_mov_b32_e32 v23, v22
	s_nop 1
	v_permlane32_swap_b32_e32 v22, v23
	v_add_f32_e32 v22, v22, v23
	v_fmamk_f32 v22, v22, 0x3a800000, v244
	v_cmp_gt_f32_e32 vcc, s81, v22
	v_mul_f32_e32 v23, 0x4f800000, v22
	s_nop 0
	v_cndmask_b32_e32 v22, v22, v23, vcc
	v_sqrt_f32_e32 v23, v22
	s_nop 0
	v_add_u32_e32 v24, -1, v23
	v_fma_f32 v25, -v24, v23, v22
	v_cmp_ge_f32_e64 s[4:5], 0, v25
	v_add_u32_e32 v25, 1, v23
	s_nop 0
	v_cndmask_b32_e64 v24, v23, v24, s[4:5]
	v_fma_f32 v23, -v25, v23, v22
	v_cmp_lt_f32_e64 s[4:5], 0, v23
	s_nop 1
	v_cndmask_b32_e64 v23, v24, v25, s[4:5]
	v_mul_f32_e32 v24, 0x37800000, v23
	v_cndmask_b32_e32 v23, v23, v24, vcc
	v_cmp_class_f32_e32 vcc, v22, v245
	s_nop 1
	v_cndmask_b32_e32 v22, v23, v22, vcc
	v_div_scale_f32 v23, s[4:5], v22, v22, 1.0
	v_rcp_f32_e32 v24, v23
	s_or_b32 s4, s22, 10
	s_ashr_i32 s5, s4, 31
	s_lshl_b64 s[12:13], s[4:5], 11
	v_fma_f32 v25, -v23, v24, 1.0
	v_fmac_f32_e32 v24, v25, v24
	v_div_scale_f32 v25, vcc, 1.0, v22, 1.0
	v_mul_f32_e32 v26, v25, v24
	v_fma_f32 v27, -v23, v26, v25
	v_fmac_f32_e32 v26, v27, v24
	s_add_u32 s4, s6, s12
	v_fma_f32 v23, -v23, v26, v25
	s_addc_u32 s5, s7, s13
	v_div_fmas_f32 v23, v23, v24, v26
	s_waitcnt vmcnt(10)
; __device__ __forceinline__ float bf_lo(unsigned v) { return __uint_as_float(v << 16); }
; __device__ __forceinline__ float bf_hi(unsigned v) { return __uint_as_float(v & 0xffff0000u); }
; __device__ __forceinline__ void sgu_item(int it, const bf16_t* GV, const bf16_t* ZU, const float* sg_, const float* sb_, const float* wsp, const float* bsp, bf16_t* CAT, unsigned char* lds, const int wv) {
;     ...
;         for (int i = 0; i < 16; ++i) { const bf16_t* row = GV + (size_t)(tok0 + 16 * wid + i) * 1024;
;             const u32x4 a = *(const u32x4*)(row + 8 * lane), c = *(const u32x4*)(row + 512 + 8 * lane);
;             float v[16];
; #pragma unroll
;             for (int k = 0; k < 4; ++k) { v[2 * k] = bf_lo(a[k]); v[2 * k + 1] = bf_hi(a[k]); v[8 + 2 * k] = bf_lo(c[k]); v[8 + 2 * k + 1] = bf_hi(c[k]); }
;             float s = 0.f;
; #pragma unroll
;             for (int k = 0; k < 16; ++k) s += v[k];
;             const float mu = wave_sum(s) * (1.0f / 1024.0f); float q = 0.f;
; #pragma unroll
;             for (int k = 0; k < 16; ++k) { const float d = v[k] - mu; q += d * d; }
;             mean[i] = mu; rstd[i] = 1.0f / sqrtf(wave_sum(q) * (1.0f / 1024.0f) + EPS); }
	v_mov_b32_e32 v24, v144
	v_mov_b32_e32 v25, v145
	v_mov_b32_e32 v26, v146
	v_mov_b32_e32 v27, v147
	v_mov_b32_e32 v28, v148
	v_mov_b32_e32 v29, v149
	v_mov_b32_e32 v30, v150
	v_mov_b32_e32 v31, v151
	v_div_fixup_f32 v22, v23, v22, 1.0
	v_lshlrev_b32_e32 v32, 16, v24
	v_and_b32_e32 v24, 0xffff0000, v24
	v_add_f32_e32 v23, 0, v32
	v_lshlrev_b32_e32 v34, 16, v25
	v_add_f32_e32 v23, v23, v24
	v_and_b32_e32 v25, 0xffff0000, v25
	v_add_f32_e32 v23, v23, v34
	v_lshlrev_b32_e32 v36, 16, v26
	v_add_f32_e32 v23, v23, v25
	v_and_b32_e32 v26, 0xffff0000, v26
	v_add_f32_e32 v23, v23, v36
	v_lshlrev_b32_e32 v38, 16, v27
	v_add_f32_e32 v23, v23, v26
	v_and_b32_e32 v27, 0xffff0000, v27
	v_add_f32_e32 v23, v23, v38
	v_lshlrev_b32_e32 v33, 16, v28
	v_add_f32_e32 v23, v23, v27
	v_and_b32_e32 v28, 0xffff0000, v28
	v_add_f32_e32 v23, v23, v33
	v_lshlrev_b32_e32 v35, 16, v29
	v_add_f32_e32 v23, v23, v28
	v_and_b32_e32 v29, 0xffff0000, v29
	v_add_f32_e32 v23, v23, v35
	v_lshlrev_b32_e32 v37, 16, v30
	v_add_f32_e32 v23, v23, v29
	v_and_b32_e32 v30, 0xffff0000, v30
	v_add_f32_e32 v23, v23, v37
	v_lshlrev_b32_e32 v39, 16, v31
	v_add_f32_e32 v23, v23, v30
	v_and_b32_e32 v31, 0xffff0000, v31
	v_add_f32_e32 v23, v23, v39
	v_add_f32_e32 v23, v23, v31
	s_nop 1
	v_add_f32_dpp v23, v23, v23 quad_perm:[1,0,3,2] row_mask:0xf bank_mask:0xf bound_ctrl:1
	s_nop 1
	v_add_f32_dpp v23, v23, v23 quad_perm:[2,3,0,1] row_mask:0xf bank_mask:0xf bound_ctrl:1
	s_nop 1
	v_add_f32_dpp v23, v23, v23 row_half_mirror row_mask:0xf bank_mask:0xf bound_ctrl:1
	s_nop 1
	v_add_f32_dpp v23, v23, v23 row_mirror row_mask:0xf bank_mask:0xf bound_ctrl:1
	ds_swizzle_b32 v40, v23 offset:swizzle(SWAP,16)
	s_waitcnt lgkmcnt(0)
	v_add_f32_e32 v23, v23, v40
	v_mov_b32_e32 v40, v23
	s_nop 1
	v_permlane32_swap_b32_e32 v23, v40
	v_add_f32_e32 v23, v23, v40
	v_fmac_f32_e32 v24, 0xba800000, v23
	v_fmac_f32_e32 v32, 0xba800000, v23
	v_mul_f32_e32 v24, v24, v24
	v_fmac_f32_e32 v24, v32, v32
	v_fmac_f32_e32 v34, 0xba800000, v23
	v_fmac_f32_e32 v24, v34, v34
	v_fmac_f32_e32 v25, 0xba800000, v23
	v_fmac_f32_e32 v24, v25, v25
	v_fmac_f32_e32 v36, 0xba800000, v23
	v_fmac_f32_e32 v24, v36, v36
	v_fmac_f32_e32 v26, 0xba800000, v23
	v_fmac_f32_e32 v24, v26, v26
	v_fmac_f32_e32 v38, 0xba800000, v23
	v_fmac_f32_e32 v24, v38, v38
	v_fmac_f32_e32 v27, 0xba800000, v23
	v_fmac_f32_e32 v24, v27, v27
	v_fmac_f32_e32 v33, 0xba800000, v23
	v_fmac_f32_e32 v24, v33, v33
	v_fmac_f32_e32 v28, 0xba800000, v23
	v_fmac_f32_e32 v24, v28, v28
	v_fmac_f32_e32 v35, 0xba800000, v23
	v_fmac_f32_e32 v24, v35, v35
	v_fmac_f32_e32 v29, 0xba800000, v23
	v_fmac_f32_e32 v24, v29, v29
	v_fmac_f32_e32 v37, 0xba800000, v23
	v_fmac_f32_e32 v24, v37, v37
	v_fmac_f32_e32 v30, 0xba800000, v23
	v_fmac_f32_e32 v24, v30, v30
	v_fmac_f32_e32 v39, 0xba800000, v23
	v_fmac_f32_e32 v24, v39, v39
	v_fmac_f32_e32 v31, 0xba800000, v23
	v_fmac_f32_e32 v24, v31, v31
	s_nop 1
	v_add_f32_dpp v24, v24, v24 quad_perm:[1,0,3,2] row_mask:0xf bank_mask:0xf bound_ctrl:1
	s_nop 1
	v_add_f32_dpp v24, v24, v24 quad_perm:[2,3,0,1] row_mask:0xf bank_mask:0xf bound_ctrl:1
	s_nop 1
	v_add_f32_dpp v24, v24, v24 row_half_mirror row_mask:0xf bank_mask:0xf bound_ctrl:1
	s_nop 1
	v_add_f32_dpp v24, v24, v24 row_mirror row_mask:0xf bank_mask:0xf bound_ctrl:1
	ds_swizzle_b32 v25, v24 offset:swizzle(SWAP,16)
	s_waitcnt lgkmcnt(0)
	v_add_f32_e32 v24, v24, v25
	v_mov_b32_e32 v25, v24
	s_nop 1
	v_permlane32_swap_b32_e32 v24, v25
	v_add_f32_e32 v24, v24, v25
	v_fmamk_f32 v24, v24, 0x3a800000, v244
	v_cmp_gt_f32_e32 vcc, s81, v24
	v_mul_f32_e32 v25, 0x4f800000, v24
	s_nop 0
	v_cndmask_b32_e32 v24, v24, v25, vcc
	v_sqrt_f32_e32 v25, v24
	s_nop 0
	v_add_u32_e32 v26, -1, v25
	v_fma_f32 v27, -v26, v25, v24
	v_cmp_ge_f32_e64 s[4:5], 0, v27
	v_add_u32_e32 v27, 1, v25
	s_nop 0
	v_cndmask_b32_e64 v26, v25, v26, s[4:5]
	v_fma_f32 v25, -v27, v25, v24
	v_cmp_lt_f32_e64 s[4:5], 0, v25
	s_nop 1
	v_cndmask_b32_e64 v25, v26, v27, s[4:5]
	v_mul_f32_e32 v26, 0x37800000, v25
	v_cndmask_b32_e32 v25, v25, v26, vcc
	v_cmp_class_f32_e32 vcc, v24, v245
	s_nop 1
	v_cndmask_b32_e32 v24, v25, v24, vcc
	v_div_scale_f32 v25, s[4:5], v24, v24, 1.0
	v_rcp_f32_e32 v26, v25
	s_or_b32 s4, s22, 11
	s_ashr_i32 s5, s4, 31
	s_lshl_b64 s[96:97], s[4:5], 11
	v_fma_f32 v27, -v25, v26, 1.0
	v_fmac_f32_e32 v26, v27, v26
	v_div_scale_f32 v27, vcc, 1.0, v24, 1.0
	v_mul_f32_e32 v28, v27, v26
	v_fma_f32 v29, -v25, v28, v27
	v_fmac_f32_e32 v28, v29, v26
	s_add_u32 s4, s6, s96
	v_fma_f32 v25, -v25, v28, v27
	s_addc_u32 s5, s7, s97
	v_div_fmas_f32 v25, v25, v26, v28
	s_waitcnt vmcnt(8)
	v_mov_b32_e32 v26, v152
	v_mov_b32_e32 v27, v153
	v_mov_b32_e32 v28, v154
	v_mov_b32_e32 v29, v155
	v_mov_b32_e32 v30, v156
	v_mov_b32_e32 v31, v157
	v_mov_b32_e32 v32, v158
	v_mov_b32_e32 v33, v159
	v_div_fixup_f32 v24, v25, v24, 1.0
	v_lshlrev_b32_e32 v34, 16, v26
	v_and_b32_e32 v26, 0xffff0000, v26
	v_add_f32_e32 v25, 0, v34
	v_lshlrev_b32_e32 v36, 16, v27
	v_add_f32_e32 v25, v25, v26
	v_and_b32_e32 v27, 0xffff0000, v27
	v_add_f32_e32 v25, v25, v36
	v_lshlrev_b32_e32 v38, 16, v28
	v_add_f32_e32 v25, v25, v27
	v_and_b32_e32 v28, 0xffff0000, v28
	v_add_f32_e32 v25, v25, v38
	v_lshlrev_b32_e32 v40, 16, v29
	v_add_f32_e32 v25, v25, v28
	v_and_b32_e32 v29, 0xffff0000, v29
	v_add_f32_e32 v25, v25, v40
	v_lshlrev_b32_e32 v35, 16, v30
	v_add_f32_e32 v25, v25, v29
	v_and_b32_e32 v30, 0xffff0000, v30
	v_add_f32_e32 v25, v25, v35
	v_lshlrev_b32_e32 v37, 16, v31
	v_add_f32_e32 v25, v25, v30
	v_and_b32_e32 v31, 0xffff0000, v31
	v_add_f32_e32 v25, v25, v37
	v_lshlrev_b32_e32 v39, 16, v32
	v_add_f32_e32 v25, v25, v31
	v_and_b32_e32 v32, 0xffff0000, v32
	v_add_f32_e32 v25, v25, v39
	v_lshlrev_b32_e32 v41, 16, v33
	v_add_f32_e32 v25, v25, v32
	v_and_b32_e32 v33, 0xffff0000, v33
	v_add_f32_e32 v25, v25, v41
	v_add_f32_e32 v25, v25, v33
	s_nop 1
	v_add_f32_dpp v25, v25, v25 quad_perm:[1,0,3,2] row_mask:0xf bank_mask:0xf bound_ctrl:1
	s_nop 1
	v_add_f32_dpp v25, v25, v25 quad_perm:[2,3,0,1] row_mask:0xf bank_mask:0xf bound_ctrl:1
	s_nop 1
	v_add_f32_dpp v25, v25, v25 row_half_mirror row_mask:0xf bank_mask:0xf bound_ctrl:1
	s_nop 1
	v_add_f32_dpp v25, v25, v25 row_mirror row_mask:0xf bank_mask:0xf bound_ctrl:1
	ds_swizzle_b32 v42, v25 offset:swizzle(SWAP,16)
	s_waitcnt lgkmcnt(0)
; __device__ __forceinline__ float bf_lo(unsigned v) { return __uint_as_float(v << 16); }
; __device__ __forceinline__ float bf_hi(unsigned v) { return __uint_as_float(v & 0xffff0000u); }
; __device__ __forceinline__ void sgu_item(int it, const bf16_t* GV, const bf16_t* ZU, const float* sg_, const float* sb_, const float* wsp, const float* bsp, bf16_t* CAT, unsigned char* lds, const int wv) {
;     ...
;         for (int i = 0; i < 16; ++i) { const bf16_t* row = GV + (size_t)(tok0 + 16 * wid + i) * 1024;
;             const u32x4 a = *(const u32x4*)(row + 8 * lane), c = *(const u32x4*)(row + 512 + 8 * lane);
;             float v[16];
; #pragma unroll
;             for (int k = 0; k < 4; ++k) { v[2 * k] = bf_lo(a[k]); v[2 * k + 1] = bf_hi(a[k]); v[8 + 2 * k] = bf_lo(c[k]); v[8 + 2 * k + 1] = bf_hi(c[k]); }
;             float s = 0.f;
; #pragma unroll
;             for (int k = 0; k < 16; ++k) s += v[k];
;             const float mu = wave_sum(s) * (1.0f / 1024.0f); float q = 0.f;
; #pragma unroll
;             for (int k = 0; k < 16; ++k) { const float d = v[k] - mu; q += d * d; }
;             mean[i] = mu; rstd[i] = 1.0f / sqrtf(wave_sum(q) * (1.0f / 1024.0f) + EPS); }
	v_add_f32_e32 v25, v25, v42
	v_mov_b32_e32 v42, v25
	s_nop 1
	v_permlane32_swap_b32_e32 v25, v42
	v_add_f32_e32 v25, v25, v42
	v_fmac_f32_e32 v26, 0xba800000, v25
	v_fmac_f32_e32 v34, 0xba800000, v25
	v_mul_f32_e32 v26, v26, v26
	v_fmac_f32_e32 v26, v34, v34
	v_fmac_f32_e32 v36, 0xba800000, v25
	v_fmac_f32_e32 v26, v36, v36
	v_fmac_f32_e32 v27, 0xba800000, v25
	v_fmac_f32_e32 v26, v27, v27
	v_fmac_f32_e32 v38, 0xba800000, v25
	v_fmac_f32_e32 v26, v38, v38
	v_fmac_f32_e32 v28, 0xba800000, v25
	v_fmac_f32_e32 v26, v28, v28
	v_fmac_f32_e32 v40, 0xba800000, v25
	v_fmac_f32_e32 v26, v40, v40
	v_fmac_f32_e32 v29, 0xba800000, v25
	v_fmac_f32_e32 v26, v29, v29
	v_fmac_f32_e32 v35, 0xba800000, v25
	v_fmac_f32_e32 v26, v35, v35
	v_fmac_f32_e32 v30, 0xba800000, v25
	v_fmac_f32_e32 v26, v30, v30
	v_fmac_f32_e32 v37, 0xba800000, v25
	v_fmac_f32_e32 v26, v37, v37
	v_fmac_f32_e32 v31, 0xba800000, v25
	v_fmac_f32_e32 v26, v31, v31
	v_fmac_f32_e32 v39, 0xba800000, v25
	v_fmac_f32_e32 v26, v39, v39
	v_fmac_f32_e32 v32, 0xba800000, v25
	v_fmac_f32_e32 v26, v32, v32
	v_fmac_f32_e32 v41, 0xba800000, v25
	v_fmac_f32_e32 v26, v41, v41
	v_fmac_f32_e32 v33, 0xba800000, v25
	v_fmac_f32_e32 v26, v33, v33
	s_nop 1
	v_add_f32_dpp v26, v26, v26 quad_perm:[1,0,3,2] row_mask:0xf bank_mask:0xf bound_ctrl:1
	s_nop 1
	v_add_f32_dpp v26, v26, v26 quad_perm:[2,3,0,1] row_mask:0xf bank_mask:0xf bound_ctrl:1
	s_nop 1
	v_add_f32_dpp v26, v26, v26 row_half_mirror row_mask:0xf bank_mask:0xf bound_ctrl:1
	s_nop 1
	v_add_f32_dpp v26, v26, v26 row_mirror row_mask:0xf bank_mask:0xf bound_ctrl:1
	ds_swizzle_b32 v27, v26 offset:swizzle(SWAP,16)
	s_waitcnt lgkmcnt(0)
	v_add_f32_e32 v26, v26, v27
	v_mov_b32_e32 v27, v26
	s_nop 1
	v_permlane32_swap_b32_e32 v26, v27
	v_add_f32_e32 v26, v26, v27
	v_fmamk_f32 v26, v26, 0x3a800000, v244
	v_cmp_gt_f32_e32 vcc, s81, v26
	v_mul_f32_e32 v27, 0x4f800000, v26
	s_nop 0
	v_cndmask_b32_e32 v26, v26, v27, vcc
	v_sqrt_f32_e32 v27, v26
	s_nop 0
	v_add_u32_e32 v28, -1, v27
	v_fma_f32 v29, -v28, v27, v26
	v_cmp_ge_f32_e64 s[4:5], 0, v29
	v_add_u32_e32 v29, 1, v27
	s_nop 0
	v_cndmask_b32_e64 v28, v27, v28, s[4:5]
	v_fma_f32 v27, -v29, v27, v26
	v_cmp_lt_f32_e64 s[4:5], 0, v27
	s_nop 1
	v_cndmask_b32_e64 v27, v28, v29, s[4:5]
	v_mul_f32_e32 v28, 0x37800000, v27
	v_cndmask_b32_e32 v27, v27, v28, vcc
	v_cmp_class_f32_e32 vcc, v26, v245
	s_nop 1
	v_cndmask_b32_e32 v26, v27, v26, vcc
	v_div_scale_f32 v27, s[4:5], v26, v26, 1.0
	v_rcp_f32_e32 v28, v27
	s_or_b32 s4, s22, 12
	s_ashr_i32 s5, s4, 31
	s_lshl_b64 s[94:95], s[4:5], 11
	v_fma_f32 v29, -v27, v28, 1.0
	v_fmac_f32_e32 v28, v29, v28
	v_div_scale_f32 v29, vcc, 1.0, v26, 1.0
	v_mul_f32_e32 v30, v29, v28
	v_fma_f32 v31, -v27, v30, v29
	v_fmac_f32_e32 v30, v31, v28
	s_add_u32 s4, s6, s94
	v_fma_f32 v27, -v27, v30, v29
	s_addc_u32 s5, s7, s95
	v_div_fmas_f32 v27, v27, v28, v30
	s_waitcnt vmcnt(6)
	v_mov_b32_e32 v28, v160
	v_mov_b32_e32 v29, v161
	v_mov_b32_e32 v30, v162
	v_mov_b32_e32 v31, v163
	v_mov_b32_e32 v32, v164
	v_mov_b32_e32 v33, v165
	v_mov_b32_e32 v34, v166
	v_mov_b32_e32 v35, v167
	v_div_fixup_f32 v26, v27, v26, 1.0
	v_lshlrev_b32_e32 v36, 16, v28
	v_and_b32_e32 v28, 0xffff0000, v28
	v_add_f32_e32 v27, 0, v36
	v_lshlrev_b32_e32 v38, 16, v29
	v_add_f32_e32 v27, v27, v28
	v_and_b32_e32 v29, 0xffff0000, v29
	v_add_f32_e32 v27, v27, v38
	v_lshlrev_b32_e32 v40, 16, v30
	v_add_f32_e32 v27, v27, v29
	v_and_b32_e32 v30, 0xffff0000, v30
	v_add_f32_e32 v27, v27, v40
	v_lshlrev_b32_e32 v42, 16, v31
	v_add_f32_e32 v27, v27, v30
	v_and_b32_e32 v31, 0xffff0000, v31
	v_add_f32_e32 v27, v27, v42
	v_lshlrev_b32_e32 v37, 16, v32
	v_add_f32_e32 v27, v27, v31
	v_and_b32_e32 v32, 0xffff0000, v32
	v_add_f32_e32 v27, v27, v37
	v_lshlrev_b32_e32 v39, 16, v33
	v_add_f32_e32 v27, v27, v32
	v_and_b32_e32 v33, 0xffff0000, v33
	v_add_f32_e32 v27, v27, v39
	v_lshlrev_b32_e32 v41, 16, v34
	v_add_f32_e32 v27, v27, v33
	v_and_b32_e32 v34, 0xffff0000, v34
	v_add_f32_e32 v27, v27, v41
	v_lshlrev_b32_e32 v43, 16, v35
	v_add_f32_e32 v27, v27, v34
	v_and_b32_e32 v35, 0xffff0000, v35
	v_add_f32_e32 v27, v27, v43
	v_add_f32_e32 v27, v27, v35
	s_nop 1
	v_add_f32_dpp v27, v27, v27 quad_perm:[1,0,3,2] row_mask:0xf bank_mask:0xf bound_ctrl:1
	s_nop 1
	v_add_f32_dpp v27, v27, v27 quad_perm:[2,3,0,1] row_mask:0xf bank_mask:0xf bound_ctrl:1
	s_nop 1
	v_add_f32_dpp v27, v27, v27 row_half_mirror row_mask:0xf bank_mask:0xf bound_ctrl:1
	s_nop 1
	v_add_f32_dpp v27, v27, v27 row_mirror row_mask:0xf bank_mask:0xf bound_ctrl:1
	ds_swizzle_b32 v44, v27 offset:swizzle(SWAP,16)
	s_waitcnt lgkmcnt(0)
	v_add_f32_e32 v27, v27, v44
	v_mov_b32_e32 v44, v27
	s_nop 1
	v_permlane32_swap_b32_e32 v27, v44
	v_add_f32_e32 v27, v27, v44
	v_fmac_f32_e32 v28, 0xba800000, v27
	v_fmac_f32_e32 v36, 0xba800000, v27
	v_mul_f32_e32 v28, v28, v28
	v_fmac_f32_e32 v28, v36, v36
	v_fmac_f32_e32 v38, 0xba800000, v27
	v_fmac_f32_e32 v28, v38, v38
	v_fmac_f32_e32 v29, 0xba800000, v27
	v_fmac_f32_e32 v28, v29, v29
	v_fmac_f32_e32 v40, 0xba800000, v27
	v_fmac_f32_e32 v28, v40, v40
	v_fmac_f32_e32 v30, 0xba800000, v27
	v_fmac_f32_e32 v28, v30, v30
	v_fmac_f32_e32 v42, 0xba800000, v27
	v_fmac_f32_e32 v28, v42, v42
	v_fmac_f32_e32 v31, 0xba800000, v27
	v_fmac_f32_e32 v28, v31, v31
	v_fmac_f32_e32 v37, 0xba800000, v27
	v_fmac_f32_e32 v28, v37, v37
	v_fmac_f32_e32 v32, 0xba800000, v27
	v_fmac_f32_e32 v28, v32, v32
	v_fmac_f32_e32 v39, 0xba800000, v27
	v_fmac_f32_e32 v28, v39, v39
	v_fmac_f32_e32 v33, 0xba800000, v27
	v_fmac_f32_e32 v28, v33, v33
	v_fmac_f32_e32 v41, 0xba800000, v27
	v_fmac_f32_e32 v28, v41, v41
	v_fmac_f32_e32 v34, 0xba800000, v27
	v_fmac_f32_e32 v28, v34, v34
	v_fmac_f32_e32 v43, 0xba800000, v27
	v_fmac_f32_e32 v28, v43, v43
	v_fmac_f32_e32 v35, 0xba800000, v27
	v_fmac_f32_e32 v28, v35, v35
	s_nop 1
	v_add_f32_dpp v28, v28, v28 quad_perm:[1,0,3,2] row_mask:0xf bank_mask:0xf bound_ctrl:1
	s_nop 1
	v_add_f32_dpp v28, v28, v28 quad_perm:[2,3,0,1] row_mask:0xf bank_mask:0xf bound_ctrl:1
	s_nop 1
	v_add_f32_dpp v28, v28, v28 row_half_mirror row_mask:0xf bank_mask:0xf bound_ctrl:1
	s_nop 1
	v_add_f32_dpp v28, v28, v28 row_mirror row_mask:0xf bank_mask:0xf bound_ctrl:1
	ds_swizzle_b32 v29, v28 offset:swizzle(SWAP,16)
	s_waitcnt lgkmcnt(0)
; __device__ __forceinline__ float bf_lo(unsigned v) { return __uint_as_float(v << 16); }
; __device__ __forceinline__ float bf_hi(unsigned v) { return __uint_as_float(v & 0xffff0000u); }
; __device__ __forceinline__ void sgu_item(int it, const bf16_t* GV, const bf16_t* ZU, const float* sg_, const float* sb_, const float* wsp, const float* bsp, bf16_t* CAT, unsigned char* lds, const int wv) {
;     ...
;         for (int i = 0; i < 16; ++i) { const bf16_t* row = GV + (size_t)(tok0 + 16 * wid + i) * 1024;
;             const u32x4 a = *(const u32x4*)(row + 8 * lane), c = *(const u32x4*)(row + 512 + 8 * lane);
;             float v[16];
; #pragma unroll
;             for (int k = 0; k < 4; ++k) { v[2 * k] = bf_lo(a[k]); v[2 * k + 1] = bf_hi(a[k]); v[8 + 2 * k] = bf_lo(c[k]); v[8 + 2 * k + 1] = bf_hi(c[k]); }
;             float s = 0.f;
; #pragma unroll
;             for (int k = 0; k < 16; ++k) s += v[k];
;             const float mu = wave_sum(s) * (1.0f / 1024.0f); float q = 0.f;
; #pragma unroll
;             for (int k = 0; k < 16; ++k) { const float d = v[k] - mu; q += d * d; }
;             mean[i] = mu; rstd[i] = 1.0f / sqrtf(wave_sum(q) * (1.0f / 1024.0f) + EPS); }
	v_add_f32_e32 v28, v28, v29
	v_mov_b32_e32 v29, v28
	s_nop 1
	v_permlane32_swap_b32_e32 v28, v29
	v_add_f32_e32 v28, v28, v29
	v_fmamk_f32 v28, v28, 0x3a800000, v244
	v_cmp_gt_f32_e32 vcc, s81, v28
	v_mul_f32_e32 v29, 0x4f800000, v28
	s_nop 0
	v_cndmask_b32_e32 v28, v28, v29, vcc
	v_sqrt_f32_e32 v29, v28
	s_nop 0
	v_add_u32_e32 v30, -1, v29
	v_fma_f32 v31, -v30, v29, v28
	v_cmp_ge_f32_e64 s[4:5], 0, v31
	v_add_u32_e32 v31, 1, v29
	s_nop 0
	v_cndmask_b32_e64 v30, v29, v30, s[4:5]
	v_fma_f32 v29, -v31, v29, v28
	v_cmp_lt_f32_e64 s[4:5], 0, v29
	s_nop 1
	v_cndmask_b32_e64 v29, v30, v31, s[4:5]
	v_mul_f32_e32 v30, 0x37800000, v29
	v_cndmask_b32_e32 v29, v29, v30, vcc
	v_cmp_class_f32_e32 vcc, v28, v245
	s_nop 1
	v_cndmask_b32_e32 v28, v29, v28, vcc
	v_div_scale_f32 v29, s[4:5], v28, v28, 1.0
	v_rcp_f32_e32 v30, v29
	s_or_b32 s4, s22, 13
	s_ashr_i32 s5, s4, 31
	s_lshl_b64 s[88:89], s[4:5], 11
	v_fma_f32 v31, -v29, v30, 1.0
	v_fmac_f32_e32 v30, v31, v30
	v_div_scale_f32 v31, vcc, 1.0, v28, 1.0
	v_mul_f32_e32 v32, v31, v30
	v_fma_f32 v33, -v29, v32, v31
	v_fmac_f32_e32 v32, v33, v30
	v_fma_f32 v29, -v29, v32, v31
	s_add_u32 s4, s6, s88
	v_div_fmas_f32 v29, v29, v30, v32
	s_addc_u32 s5, s7, s89
	v_div_fixup_f32 v36, v29, v28, 1.0
	s_waitcnt vmcnt(4)
	v_mov_b32_e32 v28, v168
	v_mov_b32_e32 v29, v169
	v_mov_b32_e32 v30, v170
	v_mov_b32_e32 v31, v171
	v_mov_b32_e32 v32, v172
	v_mov_b32_e32 v33, v173
	v_mov_b32_e32 v34, v174
	v_mov_b32_e32 v35, v175
	v_lshlrev_b32_e32 v37, 16, v28
	v_and_b32_e32 v28, 0xffff0000, v28
	v_add_f32_e32 v45, 0, v37
	v_lshlrev_b32_e32 v39, 16, v29
	v_add_f32_e32 v45, v45, v28
	v_and_b32_e32 v29, 0xffff0000, v29
	v_add_f32_e32 v45, v45, v39
	v_lshlrev_b32_e32 v41, 16, v30
	v_add_f32_e32 v45, v45, v29
	v_and_b32_e32 v30, 0xffff0000, v30
	v_add_f32_e32 v45, v45, v41
	v_lshlrev_b32_e32 v43, 16, v31
	v_add_f32_e32 v45, v45, v30
	v_and_b32_e32 v31, 0xffff0000, v31
	v_add_f32_e32 v45, v45, v43
	v_lshlrev_b32_e32 v38, 16, v32
	v_add_f32_e32 v45, v45, v31
	v_and_b32_e32 v32, 0xffff0000, v32
	v_add_f32_e32 v45, v45, v38
	v_lshlrev_b32_e32 v40, 16, v33
	v_add_f32_e32 v45, v45, v32
	v_and_b32_e32 v33, 0xffff0000, v33
	v_add_f32_e32 v45, v45, v40
	v_lshlrev_b32_e32 v42, 16, v34
	v_add_f32_e32 v45, v45, v33
	v_and_b32_e32 v34, 0xffff0000, v34
	v_add_f32_e32 v45, v45, v42
	v_lshlrev_b32_e32 v44, 16, v35
	v_add_f32_e32 v45, v45, v34
	v_and_b32_e32 v35, 0xffff0000, v35
	v_add_f32_e32 v45, v45, v44
	v_add_f32_e32 v45, v45, v35
	s_nop 1
	v_add_f32_dpp v45, v45, v45 quad_perm:[1,0,3,2] row_mask:0xf bank_mask:0xf bound_ctrl:1
	s_nop 1
	v_add_f32_dpp v45, v45, v45 quad_perm:[2,3,0,1] row_mask:0xf bank_mask:0xf bound_ctrl:1
	s_nop 1
	v_add_f32_dpp v45, v45, v45 row_half_mirror row_mask:0xf bank_mask:0xf bound_ctrl:1
	s_nop 1
	v_add_f32_dpp v45, v45, v45 row_mirror row_mask:0xf bank_mask:0xf bound_ctrl:1
	ds_swizzle_b32 v46, v45 offset:swizzle(SWAP,16)
	s_waitcnt lgkmcnt(0)
	v_add_f32_e32 v45, v45, v46
	v_mov_b32_e32 v46, v45
	s_nop 1
	v_permlane32_swap_b32_e32 v45, v46
	v_add_f32_e32 v45, v45, v46
	v_fmac_f32_e32 v28, 0xba800000, v45
	v_fmac_f32_e32 v37, 0xba800000, v45
	v_mul_f32_e32 v28, v28, v28
	v_fmac_f32_e32 v28, v37, v37
	v_fmac_f32_e32 v39, 0xba800000, v45
	v_fmac_f32_e32 v28, v39, v39
	v_fmac_f32_e32 v29, 0xba800000, v45
	v_fmac_f32_e32 v28, v29, v29
	v_fmac_f32_e32 v41, 0xba800000, v45
	v_fmac_f32_e32 v28, v41, v41
	v_fmac_f32_e32 v30, 0xba800000, v45
	v_fmac_f32_e32 v28, v30, v30
	v_fmac_f32_e32 v43, 0xba800000, v45
	v_fmac_f32_e32 v28, v43, v43
	v_fmac_f32_e32 v31, 0xba800000, v45
	v_fmac_f32_e32 v28, v31, v31
	v_fmac_f32_e32 v38, 0xba800000, v45
	v_fmac_f32_e32 v28, v38, v38
	v_fmac_f32_e32 v32, 0xba800000, v45
	v_fmac_f32_e32 v28, v32, v32
	v_fmac_f32_e32 v40, 0xba800000, v45
	v_fmac_f32_e32 v28, v40, v40
	v_fmac_f32_e32 v33, 0xba800000, v45
	v_fmac_f32_e32 v28, v33, v33
	v_fmac_f32_e32 v42, 0xba800000, v45
	v_fmac_f32_e32 v28, v42, v42
	v_fmac_f32_e32 v34, 0xba800000, v45
	v_fmac_f32_e32 v28, v34, v34
	v_fmac_f32_e32 v44, 0xba800000, v45
	v_fmac_f32_e32 v28, v44, v44
	v_fmac_f32_e32 v35, 0xba800000, v45
	v_fmac_f32_e32 v28, v35, v35
	s_nop 1
	v_add_f32_dpp v28, v28, v28 quad_perm:[1,0,3,2] row_mask:0xf bank_mask:0xf bound_ctrl:1
	s_nop 1
	v_add_f32_dpp v28, v28, v28 quad_perm:[2,3,0,1] row_mask:0xf bank_mask:0xf bound_ctrl:1
	s_nop 1
	v_add_f32_dpp v28, v28, v28 row_half_mirror row_mask:0xf bank_mask:0xf bound_ctrl:1
	s_nop 1
	v_add_f32_dpp v28, v28, v28 row_mirror row_mask:0xf bank_mask:0xf bound_ctrl:1
	ds_swizzle_b32 v29, v28 offset:swizzle(SWAP,16)
	s_waitcnt lgkmcnt(0)
	v_add_f32_e32 v28, v28, v29
	v_mov_b32_e32 v29, v28
	s_nop 1
	v_permlane32_swap_b32_e32 v28, v29
	v_add_f32_e32 v28, v28, v29
	v_fmamk_f32 v28, v28, 0x3a800000, v244
	v_cmp_gt_f32_e32 vcc, s81, v28
	v_mul_f32_e32 v29, 0x4f800000, v28
	s_nop 0
	v_cndmask_b32_e32 v28, v28, v29, vcc
	v_sqrt_f32_e32 v29, v28
	s_nop 0
	v_add_u32_e32 v30, -1, v29
	v_fma_f32 v31, -v30, v29, v28
	v_cmp_ge_f32_e64 s[4:5], 0, v31
	v_add_u32_e32 v31, 1, v29
	s_nop 0
	v_cndmask_b32_e64 v30, v29, v30, s[4:5]
	v_fma_f32 v29, -v31, v29, v28
	v_cmp_lt_f32_e64 s[4:5], 0, v29
	s_nop 1
	v_cndmask_b32_e64 v29, v30, v31, s[4:5]
	v_mul_f32_e32 v30, 0x37800000, v29
	v_cndmask_b32_e32 v29, v29, v30, vcc
	v_cmp_class_f32_e32 vcc, v28, v245
	s_nop 1
	v_cndmask_b32_e32 v28, v29, v28, vcc
	v_div_scale_f32 v29, s[4:5], v28, v28, 1.0
	v_rcp_f32_e32 v30, v29
	s_or_b32 s4, s22, 14
	s_ashr_i32 s5, s4, 31
	s_lshl_b64 s[86:87], s[4:5], 11
	v_fma_f32 v31, -v29, v30, 1.0
	v_fmac_f32_e32 v30, v31, v30
	v_div_scale_f32 v31, vcc, 1.0, v28, 1.0
	v_mul_f32_e32 v32, v31, v30
	v_fma_f32 v33, -v29, v32, v31
	v_fmac_f32_e32 v32, v33, v30
	v_fma_f32 v29, -v29, v32, v31
	s_add_u32 s4, s6, s86
	v_div_fmas_f32 v29, v29, v30, v32
	s_addc_u32 s5, s7, s87
	v_div_fixup_f32 v37, v29, v28, 1.0
	s_waitcnt vmcnt(2)
; __device__ __forceinline__ float bf_lo(unsigned v) { return __uint_as_float(v << 16); }
; __device__ __forceinline__ float bf_hi(unsigned v) { return __uint_as_float(v & 0xffff0000u); }
; __device__ __forceinline__ void sgu_item(int it, const bf16_t* GV, const bf16_t* ZU, const float* sg_, const float* sb_, const float* wsp, const float* bsp, bf16_t* CAT, unsigned char* lds, const int wv) {
;     ...
;         for (int i = 0; i < 16; ++i) { const bf16_t* row = GV + (size_t)(tok0 + 16 * wid + i) * 1024;
;             const u32x4 a = *(const u32x4*)(row + 8 * lane), c = *(const u32x4*)(row + 512 + 8 * lane);
;             float v[16];
; #pragma unroll
;             for (int k = 0; k < 4; ++k) { v[2 * k] = bf_lo(a[k]); v[2 * k + 1] = bf_hi(a[k]); v[8 + 2 * k] = bf_lo(c[k]); v[8 + 2 * k + 1] = bf_hi(c[k]); }
;             float s = 0.f;
; #pragma unroll
;             for (int k = 0; k < 16; ++k) s += v[k];
;             const float mu = wave_sum(s) * (1.0f / 1024.0f); float q = 0.f;
; #pragma unroll
;             for (int k = 0; k < 16; ++k) { const float d = v[k] - mu; q += d * d; }
;             mean[i] = mu; rstd[i] = 1.0f / sqrtf(wave_sum(q) * (1.0f / 1024.0f) + EPS); }
	v_mov_b32_e32 v28, v176
	v_mov_b32_e32 v29, v177
	v_mov_b32_e32 v30, v178
	v_mov_b32_e32 v31, v179
	v_mov_b32_e32 v32, v180
	v_mov_b32_e32 v33, v181
	v_mov_b32_e32 v34, v182
	v_mov_b32_e32 v35, v183
	v_lshlrev_b32_e32 v38, 16, v28
	v_and_b32_e32 v28, 0xffff0000, v28
	v_add_f32_e32 v47, 0, v38
	v_lshlrev_b32_e32 v40, 16, v29
	v_add_f32_e32 v47, v47, v28
	v_and_b32_e32 v29, 0xffff0000, v29
	v_add_f32_e32 v47, v47, v40
	v_lshlrev_b32_e32 v42, 16, v30
	v_add_f32_e32 v47, v47, v29
	v_and_b32_e32 v30, 0xffff0000, v30
	v_add_f32_e32 v47, v47, v42
	v_lshlrev_b32_e32 v44, 16, v31
	v_add_f32_e32 v47, v47, v30
	v_and_b32_e32 v31, 0xffff0000, v31
	v_add_f32_e32 v47, v47, v44
	v_lshlrev_b32_e32 v39, 16, v32
	v_add_f32_e32 v47, v47, v31
	v_and_b32_e32 v32, 0xffff0000, v32
	v_add_f32_e32 v47, v47, v39
	v_lshlrev_b32_e32 v41, 16, v33
	v_add_f32_e32 v47, v47, v32
	v_and_b32_e32 v33, 0xffff0000, v33
	v_add_f32_e32 v47, v47, v41
	v_lshlrev_b32_e32 v43, 16, v34
	v_add_f32_e32 v47, v47, v33
	v_and_b32_e32 v34, 0xffff0000, v34
	v_add_f32_e32 v47, v47, v43
	v_lshlrev_b32_e32 v46, 16, v35
	v_add_f32_e32 v47, v47, v34
	v_and_b32_e32 v35, 0xffff0000, v35
	v_add_f32_e32 v47, v47, v46
	v_add_f32_e32 v47, v47, v35
	s_nop 1
	v_add_f32_dpp v47, v47, v47 quad_perm:[1,0,3,2] row_mask:0xf bank_mask:0xf bound_ctrl:1
	s_nop 1
	v_add_f32_dpp v47, v47, v47 quad_perm:[2,3,0,1] row_mask:0xf bank_mask:0xf bound_ctrl:1
	s_nop 1
	v_add_f32_dpp v47, v47, v47 row_half_mirror row_mask:0xf bank_mask:0xf bound_ctrl:1
	s_nop 1
	v_add_f32_dpp v47, v47, v47 row_mirror row_mask:0xf bank_mask:0xf bound_ctrl:1
	ds_swizzle_b32 v48, v47 offset:swizzle(SWAP,16)
	s_waitcnt lgkmcnt(0)
	v_add_f32_e32 v47, v47, v48
	v_mov_b32_e32 v48, v47
	s_nop 1
	v_permlane32_swap_b32_e32 v47, v48
	v_add_f32_e32 v47, v47, v48
	v_fmac_f32_e32 v28, 0xba800000, v47
	v_fmac_f32_e32 v38, 0xba800000, v47
	v_mul_f32_e32 v28, v28, v28
	v_fmac_f32_e32 v28, v38, v38
	v_fmac_f32_e32 v40, 0xba800000, v47
	v_fmac_f32_e32 v28, v40, v40
	v_fmac_f32_e32 v29, 0xba800000, v47
	v_fmac_f32_e32 v28, v29, v29
	v_fmac_f32_e32 v42, 0xba800000, v47
	v_fmac_f32_e32 v28, v42, v42
	v_fmac_f32_e32 v30, 0xba800000, v47
	v_fmac_f32_e32 v28, v30, v30
	v_fmac_f32_e32 v44, 0xba800000, v47
	v_fmac_f32_e32 v28, v44, v44
	v_fmac_f32_e32 v31, 0xba800000, v47
	v_fmac_f32_e32 v28, v31, v31
	v_fmac_f32_e32 v39, 0xba800000, v47
	v_fmac_f32_e32 v28, v39, v39
	v_fmac_f32_e32 v32, 0xba800000, v47
	v_fmac_f32_e32 v28, v32, v32
	v_fmac_f32_e32 v41, 0xba800000, v47
	v_fmac_f32_e32 v28, v41, v41
	v_fmac_f32_e32 v33, 0xba800000, v47
	v_fmac_f32_e32 v28, v33, v33
	v_fmac_f32_e32 v43, 0xba800000, v47
	v_fmac_f32_e32 v28, v43, v43
	v_fmac_f32_e32 v34, 0xba800000, v47
	v_fmac_f32_e32 v28, v34, v34
	v_fmac_f32_e32 v46, 0xba800000, v47
	v_fmac_f32_e32 v28, v46, v46
	v_fmac_f32_e32 v35, 0xba800000, v47
	v_fmac_f32_e32 v28, v35, v35
	s_nop 1
	v_add_f32_dpp v28, v28, v28 quad_perm:[1,0,3,2] row_mask:0xf bank_mask:0xf bound_ctrl:1
	s_nop 1
	v_add_f32_dpp v28, v28, v28 quad_perm:[2,3,0,1] row_mask:0xf bank_mask:0xf bound_ctrl:1
	s_nop 1
	v_add_f32_dpp v28, v28, v28 row_half_mirror row_mask:0xf bank_mask:0xf bound_ctrl:1
	s_nop 1
	v_add_f32_dpp v28, v28, v28 row_mirror row_mask:0xf bank_mask:0xf bound_ctrl:1
	ds_swizzle_b32 v29, v28 offset:swizzle(SWAP,16)
	s_waitcnt lgkmcnt(0)
	v_add_f32_e32 v28, v28, v29
	v_mov_b32_e32 v29, v28
	s_nop 1
	v_permlane32_swap_b32_e32 v28, v29
	v_add_f32_e32 v28, v28, v29
	v_fmamk_f32 v28, v28, 0x3a800000, v244
	v_cmp_gt_f32_e32 vcc, s81, v28
	v_mul_f32_e32 v29, 0x4f800000, v28
	s_nop 0
	v_cndmask_b32_e32 v28, v28, v29, vcc
	v_sqrt_f32_e32 v29, v28
	s_nop 0
	v_add_u32_e32 v30, -1, v29
	v_fma_f32 v31, -v30, v29, v28
	v_cmp_ge_f32_e64 s[4:5], 0, v31
	v_add_u32_e32 v31, 1, v29
	s_nop 0
	v_cndmask_b32_e64 v30, v29, v30, s[4:5]
	v_fma_f32 v29, -v31, v29, v28
	v_cmp_lt_f32_e64 s[4:5], 0, v29
	s_nop 1
	v_cndmask_b32_e64 v29, v30, v31, s[4:5]
	v_mul_f32_e32 v30, 0x37800000, v29
	v_cndmask_b32_e32 v29, v29, v30, vcc
	v_cmp_class_f32_e32 vcc, v28, v245
	s_nop 1
	v_cndmask_b32_e32 v28, v29, v28, vcc
	v_div_scale_f32 v29, s[4:5], v28, v28, 1.0
	v_rcp_f32_e32 v30, v29
	s_or_b32 s4, s22, 15
	s_ashr_i32 s5, s4, 31
	s_lshl_b64 s[22:23], s[4:5], 11
	v_fma_f32 v31, -v29, v30, 1.0
	v_fmac_f32_e32 v30, v31, v30
	v_div_scale_f32 v31, vcc, 1.0, v28, 1.0
	v_mul_f32_e32 v32, v31, v30
	v_fma_f32 v33, -v29, v32, v31
	v_fmac_f32_e32 v32, v33, v30
	v_fma_f32 v29, -v29, v32, v31
	s_add_u32 s4, s6, s22
	v_div_fmas_f32 v29, v29, v30, v32
	s_addc_u32 s5, s7, s23
	v_div_fixup_f32 v38, v29, v28, 1.0
	s_waitcnt vmcnt(0)
	v_mov_b32_e32 v28, v184
	v_mov_b32_e32 v29, v185
	v_mov_b32_e32 v30, v186
	v_mov_b32_e32 v31, v187
	v_mov_b32_e32 v32, v188
	v_mov_b32_e32 v33, v189
	v_mov_b32_e32 v34, v190
	v_mov_b32_e32 v35, v191
	s_and_b32 s38, s8, 0x380
	s_lshl_b32 s1, s9, 5
	s_add_i32 s1, s1, 0
	s_add_i32 s8, s8, s65
	v_lshlrev_b32_e32 v3, 16, v28
	v_and_b32_e32 v28, 0xffff0000, v28
	v_add_f32_e32 v48, 0, v3
	v_lshlrev_b32_e32 v40, 16, v29
	v_add_f32_e32 v48, v48, v28
	v_and_b32_e32 v29, 0xffff0000, v29
	v_add_f32_e32 v48, v48, v40
	v_lshlrev_b32_e32 v42, 16, v30
	v_add_f32_e32 v48, v48, v29
	v_and_b32_e32 v30, 0xffff0000, v30
	v_add_f32_e32 v48, v48, v42
	v_lshlrev_b32_e32 v44, 16, v31
	v_add_f32_e32 v48, v48, v30
	v_and_b32_e32 v31, 0xffff0000, v31
	v_add_f32_e32 v48, v48, v44
	v_lshlrev_b32_e32 v39, 16, v32
	v_add_f32_e32 v48, v48, v31
	v_and_b32_e32 v32, 0xffff0000, v32
	v_add_f32_e32 v48, v48, v39
	v_lshlrev_b32_e32 v41, 16, v33
	v_add_f32_e32 v48, v48, v32
	v_and_b32_e32 v33, 0xffff0000, v33
	v_add_f32_e32 v48, v48, v41
	v_lshlrev_b32_e32 v43, 16, v34
	v_add_f32_e32 v48, v48, v33
	v_and_b32_e32 v34, 0xffff0000, v34
	v_add_f32_e32 v48, v48, v43
	v_lshlrev_b32_e32 v46, 16, v35
	v_add_f32_e32 v48, v48, v34
	v_and_b32_e32 v35, 0xffff0000, v35
	v_add_f32_e32 v48, v48, v46
	v_add_f32_e32 v48, v48, v35
	s_nop 1
	v_add_f32_dpp v48, v48, v48 quad_perm:[1,0,3,2] row_mask:0xf bank_mask:0xf bound_ctrl:1
	s_nop 1
	v_add_f32_dpp v48, v48, v48 quad_perm:[2,3,0,1] row_mask:0xf bank_mask:0xf bound_ctrl:1
	s_nop 1
	v_add_f32_dpp v48, v48, v48 row_half_mirror row_mask:0xf bank_mask:0xf bound_ctrl:1
	s_nop 1
	v_add_f32_dpp v48, v48, v48 row_mirror row_mask:0xf bank_mask:0xf bound_ctrl:1
	ds_swizzle_b32 v49, v48 offset:swizzle(SWAP,16)
	s_waitcnt lgkmcnt(0)
; __device__ __forceinline__ float bf_lo(unsigned v) { return __uint_as_float(v << 16); }
; __device__ __forceinline__ float bf_hi(unsigned v) { return __uint_as_float(v & 0xffff0000u); }
; __device__ __forceinline__ void sgu_item(int it, const bf16_t* GV, const bf16_t* ZU, const float* sg_, const float* sb_, const float* wsp, const float* bsp, bf16_t* CAT, unsigned char* lds, const int wv) {
;     ...
;             const float mu = wave_sum(s) * (1.0f / 1024.0f); float q = 0.f;
; #pragma unroll
;             for (int k = 0; k < 16; ++k) { const float d = v[k] - mu; q += d * d; }
;             mean[i] = mu; rstd[i] = 1.0f / sqrtf(wave_sum(q) * (1.0f / 1024.0f) + EPS); }
;         const int c0 = g * 128 + 2 * lane;
;         const f32x2 sgv = *(const f32x2*)(sg_ + c0), sbv = *(const f32x2*)(sb_ + c0);
;         float z0[16], z1[16];
; #pragma unroll
;         for (int i = 0; i < 16; ++i) { const unsigned v = *(const unsigned*)(GV + (size_t)(tok0 + 16 * wid + i) * 1024 + c0);
;             z0[i] = (bf_lo(v) - mean[i]) * rstd[i] * sgv.x + sbv.x; z1[i] = (bf_hi(v) - mean[i]) * rstd[i] * sgv.y + sbv.y; }
	v_add_f32_e32 v48, v48, v49
	v_mov_b32_e32 v49, v48
	s_nop 1
	v_permlane32_swap_b32_e32 v48, v49
	v_add_f32_e32 v48, v48, v49
	v_fmac_f32_e32 v28, 0xba800000, v48
	v_fmac_f32_e32 v3, 0xba800000, v48
	v_mul_f32_e32 v28, v28, v28
	v_fmac_f32_e32 v28, v3, v3
	v_fmac_f32_e32 v40, 0xba800000, v48
	v_fmac_f32_e32 v28, v40, v40
	v_fmac_f32_e32 v29, 0xba800000, v48
	v_fmac_f32_e32 v28, v29, v29
	v_fmac_f32_e32 v42, 0xba800000, v48
	v_fmac_f32_e32 v28, v42, v42
	v_fmac_f32_e32 v30, 0xba800000, v48
	v_fmac_f32_e32 v28, v30, v30
	v_fmac_f32_e32 v44, 0xba800000, v48
	v_fmac_f32_e32 v28, v44, v44
	v_fmac_f32_e32 v31, 0xba800000, v48
	v_fmac_f32_e32 v28, v31, v31
	v_fmac_f32_e32 v39, 0xba800000, v48
	v_fmac_f32_e32 v28, v39, v39
	v_fmac_f32_e32 v32, 0xba800000, v48
	v_fmac_f32_e32 v28, v32, v32
	v_fmac_f32_e32 v41, 0xba800000, v48
	v_fmac_f32_e32 v28, v41, v41
	v_fmac_f32_e32 v33, 0xba800000, v48
	v_fmac_f32_e32 v28, v33, v33
	v_fmac_f32_e32 v43, 0xba800000, v48
	v_fmac_f32_e32 v28, v43, v43
	v_fmac_f32_e32 v34, 0xba800000, v48
	v_fmac_f32_e32 v28, v34, v34
	v_fmac_f32_e32 v46, 0xba800000, v48
	v_fmac_f32_e32 v28, v46, v46
	v_fmac_f32_e32 v35, 0xba800000, v48
	v_fmac_f32_e32 v28, v35, v35
	v_lshlrev_b32_e32 v39, 1, v0
	v_or_b32_e32 v0, s38, v39
	v_add_f32_dpp v3, v28, v28 quad_perm:[1,0,3,2] row_mask:0xf bank_mask:0xf bound_ctrl:1
	v_lshlrev_b32_e32 v210, 1, v0
	s_nop 0
	v_add_f32_dpp v3, v3, v3 quad_perm:[2,3,0,1] row_mask:0xf bank_mask:0xf bound_ctrl:1
	s_nop 1
	v_add_f32_dpp v3, v3, v3 row_half_mirror row_mask:0xf bank_mask:0xf bound_ctrl:1
	s_nop 1
	v_add_f32_dpp v3, v3, v3 row_mirror row_mask:0xf bank_mask:0xf bound_ctrl:1
	ds_swizzle_b32 v28, v3 offset:swizzle(SWAP,16)
	s_waitcnt lgkmcnt(0)
	v_add_f32_e32 v3, v3, v28
	v_mov_b32_e32 v28, v3
	s_nop 1
	v_permlane32_swap_b32_e32 v3, v28
	v_add_f32_e32 v3, v3, v28
	v_fmamk_f32 v3, v3, 0x3a800000, v244
	v_cmp_gt_f32_e32 vcc, s81, v3
	v_mul_f32_e32 v28, 0x4f800000, v3
	s_nop 0
	v_cndmask_b32_e32 v3, v3, v28, vcc
	v_sqrt_f32_e32 v28, v3
	s_nop 0
	v_add_u32_e32 v29, -1, v28
	v_fma_f32 v30, -v29, v28, v3
	v_cmp_ge_f32_e64 s[4:5], 0, v30
	v_add_u32_e32 v30, 1, v28
	s_nop 0
	v_cndmask_b32_e64 v29, v28, v29, s[4:5]
	v_fma_f32 v28, -v30, v28, v3
	v_cmp_lt_f32_e64 s[4:5], 0, v28
	s_nop 1
	v_cndmask_b32_e64 v28, v29, v30, s[4:5]
	v_mul_f32_e32 v29, 0x37800000, v28
	v_cndmask_b32_e32 v28, v28, v29, vcc
	v_cmp_class_f32_e32 vcc, v3, v245
	s_nop 1
	v_cndmask_b32_e32 v3, v28, v3, vcc
	v_div_scale_f32 v28, s[4:5], v3, v3, 1.0
	v_rcp_f32_e32 v29, v28
	v_readlane_b32 s4, v255, 39
	v_readlane_b32 s5, v255, 40
	v_fma_f32 v30, -v28, v29, 1.0
	v_fmac_f32_e32 v29, v30, v29
	v_div_scale_f32 v30, vcc, 1.0, v3, 1.0
	v_mul_f32_e32 v31, v30, v29
	v_fma_f32 v32, -v28, v31, v30
	v_fmac_f32_e32 v31, v32, v29
	v_fma_f32 v28, -v28, v31, v30
	v_lshl_add_u64 v[32:33], s[6:7], 0, v[210:211]
	v_div_fmas_f32 v28, v28, v29, v31
	v_lshlrev_b32_e32 v30, 2, v0
	v_lshl_add_u64 v[34:35], v[32:33], 0, s[16:17]
	v_div_fixup_f32 v3, v28, v3, 1.0
	s_movk_i32 s98, 0x1000
	s_mov_b32 s99, 0
	v_lshl_add_u64 v[52:53], v[34:35], 0, s[98:99]
	s_movk_i32 s98, 0x2000
	v_lshl_add_u64 v[54:55], v[52:53], 0, s[98:99]
	v_lshl_add_u64 v[56:57], v[54:55], 0, s[98:99]
	v_lshl_add_u64 v[58:59], v[56:57], 0, s[98:99]
	global_load_dword v192, v[52:53], off offset:-4096
	global_load_dword v193, v[52:53], off offset:-2048
	global_load_dword v194, v[52:53], off
	global_load_dword v195, v[52:53], off offset:2048
	global_load_dword v196, v[54:55], off offset:-4096
	global_load_dword v197, v[54:55], off offset:-2048
	global_load_dword v198, v[54:55], off
	global_load_dword v199, v[54:55], off offset:2048
	global_load_dword v200, v[56:57], off offset:-4096
	global_load_dword v201, v[56:57], off offset:-2048
	global_load_dword v202, v[56:57], off
	global_load_dword v203, v[56:57], off offset:2048
	global_load_dword v204, v[58:59], off offset:-4096
	global_load_dword v205, v[58:59], off offset:-2048
	global_load_dword v206, v[58:59], off
	global_load_dword v207, v[58:59], off offset:2048
	global_load_dwordx2 v[28:29], v30, s[14:15]
	s_nop 0
	global_load_dwordx2 v[30:31], v30, s[24:25]
	s_nop 0
	s_waitcnt vmcnt(0)
	v_mov_b32_e32 v0, v192
	v_lshlrev_b32_e32 v34, 16, v0
	v_and_b32_e32 v0, 0xffff0000, v0
	v_fmac_f32_e32 v0, 0xba800000, v1
	v_mul_f32_e32 v0, v2, v0
	v_fmac_f32_e32 v34, 0xba800000, v1
	v_fma_f32 v35, v29, v0, v31
	v_lshl_add_u64 v[0:1], v[32:33], 0, s[20:21]
	v_mov_b32_e32 v0, v193
	v_mul_f32_e32 v34, v2, v34
	v_fma_f32 v34, v28, v34, v30
	s_waitcnt vmcnt(0)
	v_lshlrev_b32_e32 v1, 16, v0
	v_and_b32_e32 v0, 0xffff0000, v0
	v_fmac_f32_e32 v1, 0xba800000, v4
	v_fmac_f32_e32 v0, 0xba800000, v4
	v_mul_f32_e32 v1, v5, v1
	v_mul_f32_e32 v0, v5, v0
	v_fma_f32 v2, v28, v1, v30
	v_fma_f32 v40, v29, v0, v31
	v_lshl_add_u64 v[0:1], v[32:33], 0, s[28:29]
	v_mov_b32_e32 v0, v194
	s_waitcnt vmcnt(0)
	v_lshlrev_b32_e32 v1, 16, v0
	v_and_b32_e32 v0, 0xffff0000, v0
	v_fmac_f32_e32 v1, 0xba800000, v6
	v_fmac_f32_e32 v0, 0xba800000, v6
	v_mul_f32_e32 v1, v7, v1
	v_mul_f32_e32 v0, v7, v0
	v_fma_f32 v4, v28, v1, v30
	v_fma_f32 v41, v29, v0, v31
	v_lshl_add_u64 v[0:1], v[32:33], 0, s[30:31]
	v_mov_b32_e32 v0, v195
	s_waitcnt vmcnt(0)
	v_lshlrev_b32_e32 v1, 16, v0
	v_and_b32_e32 v0, 0xffff0000, v0
	v_fmac_f32_e32 v1, 0xba800000, v8
	v_fmac_f32_e32 v0, 0xba800000, v8
	v_mul_f32_e32 v1, v9, v1
	v_mul_f32_e32 v0, v9, v0
	v_fma_f32 v5, v28, v1, v30
	v_fma_f32 v9, v29, v0, v31
	v_lshl_add_u64 v[0:1], v[32:33], 0, s[34:35]
	v_mov_b32_e32 v0, v196
	s_waitcnt vmcnt(0)
; #define LAS __attribute__((address_space(3)))
; __device__ __forceinline__ unsigned cvt_pk_bf16(float lo, float hi) { unsigned r; asm volatile("v_cvt_pk_bf16_f32 %0, %1, %2" : "=v"(r) : "v"(lo), "v"(hi)); return r; }
; __device__ __forceinline__ float bf_lo(unsigned v) { return __uint_as_float(v << 16); }
; __device__ __forceinline__ float bf_hi(unsigned v) { return __uint_as_float(v & 0xffff0000u); }
; __device__ __forceinline__ void sgu_item(int it, const bf16_t* GV, const bf16_t* ZU, const float* sg_, const float* sb_, const float* wsp, const float* bsp, bf16_t* CAT, unsigned char* lds, const int wv) {
;     ...
;         for (int i = 0; i < 16; ++i) { const unsigned v = *(const unsigned*)(GV + (size_t)(tok0 + 16 * wid + i) * 1024 + c0);
;             z0[i] = (bf_lo(v) - mean[i]) * rstd[i] * sgv.x + sbv.x; z1[i] = (bf_hi(v) - mean[i]) * rstd[i] * sgv.y + sbv.y; }
;         u32x4 w0a, w0b, w1a, w1b;
;         w0a.x = cvt_pk_bf16(z0[0], z0[1]); w0a.y = cvt_pk_bf16(z0[2], z0[3]); w0a.z = cvt_pk_bf16(z0[4], z0[5]); w0a.w = cvt_pk_bf16(z0[6], z0[7]);
;         w0b.x = cvt_pk_bf16(z0[8], z0[9]); w0b.y = cvt_pk_bf16(z0[10], z0[11]); w0b.z = cvt_pk_bf16(z0[12], z0[13]); w0b.w = cvt_pk_bf16(z0[14], z0[15]);
;         w1a.x = cvt_pk_bf16(z1[0], z1[1]); w1a.y = cvt_pk_bf16(z1[2], z1[3]); w1a.z = cvt_pk_bf16(z1[4], z1[5]); w1a.w = cvt_pk_bf16(z1[6], z1[7]);
;         w1b.x = cvt_pk_bf16(z1[8], z1[9]); w1b.y = cvt_pk_bf16(z1[10], z1[11]); w1b.z = cvt_pk_bf16(z1[12], z1[13]); w1b.w = cvt_pk_bf16(z1[14], z1[15]);
;         const int x0 = 2 * lane, s0 = (x0 & ~31) + 16 * ((x0 >> 2) & 1) + 4 * ((x0 & 31) >> 3) + (x0 & 3);
;         LAS unsigned char* r0 = ZT + s0 * 272 + 32 * wid;
;         *(LAS u32x4*)(r0) = w0a; *(LAS u32x4*)(r0 + 16) = w0b; *(LAS u32x4*)(r0 + 272) = w1a; *(LAS u32x4*)(r0 + 272 + 16) = w1b;
;     }
;     __syncthreads();
;     const int pl = lane & 15, kg = lane >> 4, p = 16 * wid + pl;
;     bf16x8 Y[4];
; #pragma unroll
;     for (int ks = 0; ks < 4; ++ks) { const float* wp = wsp + ((size_t)g * 128 + p) * 128 + 32 * ks + 8 * kg;
	v_lshlrev_b32_e32 v1, 16, v0
	v_and_b32_e32 v0, 0xffff0000, v0
	v_fmac_f32_e32 v1, 0xba800000, v10
	v_fmac_f32_e32 v0, 0xba800000, v10
	v_mul_f32_e32 v1, v11, v1
	v_mul_f32_e32 v0, v11, v0
	v_fma_f32 v6, v28, v1, v30
	v_fma_f32 v10, v29, v0, v31
	v_lshl_add_u64 v[0:1], v[32:33], 0, s[26:27]
	v_mov_b32_e32 v0, v197
	s_load_dwordx2 s[26:27], s[82:83], 0xa0
	s_waitcnt vmcnt(0)
	v_lshlrev_b32_e32 v1, 16, v0
	v_and_b32_e32 v0, 0xffff0000, v0
	v_fmac_f32_e32 v1, 0xba800000, v12
	v_fmac_f32_e32 v0, 0xba800000, v12
	v_mul_f32_e32 v1, v13, v1
	v_mul_f32_e32 v0, v13, v0
	v_fma_f32 v7, v28, v1, v30
	v_fma_f32 v11, v29, v0, v31
	v_lshl_add_u64 v[0:1], v[32:33], 0, s[36:37]
	v_mov_b32_e32 v0, v198
	s_waitcnt vmcnt(0)
	v_lshlrev_b32_e32 v1, 16, v0
	v_and_b32_e32 v0, 0xffff0000, v0
	v_fmac_f32_e32 v1, 0xba800000, v14
	v_fmac_f32_e32 v0, 0xba800000, v14
	v_mul_f32_e32 v1, v15, v1
	v_mul_f32_e32 v0, v15, v0
	v_fma_f32 v8, v28, v1, v30
	v_fma_f32 v12, v29, v0, v31
	v_lshl_add_u64 v[0:1], v[32:33], 0, s[42:43]
	v_mov_b32_e32 v0, v199
	s_waitcnt vmcnt(0)
	v_lshlrev_b32_e32 v1, 16, v0
	v_and_b32_e32 v0, 0xffff0000, v0
	v_fmac_f32_e32 v1, 0xba800000, v17
	v_fmac_f32_e32 v0, 0xba800000, v17
	v_mul_f32_e32 v1, v18, v1
	v_mul_f32_e32 v0, v18, v0
	v_fma_f32 v13, v28, v1, v30
	v_fma_f32 v14, v29, v0, v31
	v_lshl_add_u64 v[0:1], v[32:33], 0, s[44:45]
	v_mov_b32_e32 v0, v200
	v_readlane_b32 s44, v255, 26
	s_add_i32 s92, s92, s44
	s_waitcnt vmcnt(0)
	v_lshlrev_b32_e32 v1, 16, v0
	v_and_b32_e32 v0, 0xffff0000, v0
	v_fmac_f32_e32 v1, 0xba800000, v19
	v_fmac_f32_e32 v0, 0xba800000, v19
	v_mul_f32_e32 v1, v20, v1
	v_mul_f32_e32 v0, v20, v0
	v_fma_f32 v15, v28, v1, v30
	v_fma_f32 v17, v29, v0, v31
	v_lshl_add_u64 v[0:1], v[32:33], 0, s[10:11]
	v_mov_b32_e32 v0, v201
	s_waitcnt vmcnt(0)
	v_lshlrev_b32_e32 v1, 16, v0
	v_and_b32_e32 v0, 0xffff0000, v0
	v_fmac_f32_e32 v1, 0xba800000, v21
	v_fmac_f32_e32 v0, 0xba800000, v21
	v_mul_f32_e32 v1, v22, v1
	v_mul_f32_e32 v0, v22, v0
	v_fma_f32 v18, v28, v1, v30
	v_fma_f32 v19, v29, v0, v31
	v_lshl_add_u64 v[0:1], v[32:33], 0, s[12:13]
	v_mov_b32_e32 v0, v202
	s_waitcnt vmcnt(0)
	v_lshlrev_b32_e32 v1, 16, v0
	v_and_b32_e32 v0, 0xffff0000, v0
	v_fmac_f32_e32 v1, 0xba800000, v23
	v_fmac_f32_e32 v0, 0xba800000, v23
	v_mul_f32_e32 v1, v24, v1
	v_mul_f32_e32 v0, v24, v0
	v_fma_f32 v20, v28, v1, v30
	v_fma_f32 v21, v29, v0, v31
	v_lshl_add_u64 v[0:1], v[32:33], 0, s[96:97]
	v_mov_b32_e32 v0, v203
	s_waitcnt vmcnt(0)
	v_lshlrev_b32_e32 v1, 16, v0
	v_and_b32_e32 v0, 0xffff0000, v0
	v_fmac_f32_e32 v1, 0xba800000, v25
	v_fmac_f32_e32 v0, 0xba800000, v25
	v_mul_f32_e32 v1, v26, v1
	v_mul_f32_e32 v0, v26, v0
	v_fma_f32 v22, v28, v1, v30
	v_fma_f32 v23, v29, v0, v31
	v_lshl_add_u64 v[0:1], v[32:33], 0, s[94:95]
	v_mov_b32_e32 v0, v204
	s_waitcnt vmcnt(0)
	v_lshlrev_b32_e32 v1, 16, v0
	v_and_b32_e32 v0, 0xffff0000, v0
	v_fmac_f32_e32 v1, 0xba800000, v27
	v_fmac_f32_e32 v0, 0xba800000, v27
	v_mul_f32_e32 v1, v36, v1
	v_mul_f32_e32 v0, v36, v0
	v_fma_f32 v24, v28, v1, v30
	v_fma_f32 v25, v29, v0, v31
	v_lshl_add_u64 v[0:1], v[32:33], 0, s[88:89]
	v_mov_b32_e32 v0, v205
	s_waitcnt vmcnt(0)
	v_lshlrev_b32_e32 v1, 16, v0
	v_and_b32_e32 v0, 0xffff0000, v0
	v_fmac_f32_e32 v1, 0xba800000, v45
	v_fmac_f32_e32 v0, 0xba800000, v45
	v_mul_f32_e32 v1, v37, v1
	v_mul_f32_e32 v0, v37, v0
	v_fma_f32 v26, v28, v1, v30
	v_fma_f32 v27, v29, v0, v31
	v_lshl_add_u64 v[0:1], v[32:33], 0, s[86:87]
	v_mov_b32_e32 v0, v206
	s_waitcnt vmcnt(0)
	v_lshlrev_b32_e32 v1, 16, v0
	v_and_b32_e32 v0, 0xffff0000, v0
	v_fmac_f32_e32 v1, 0xba800000, v47
	v_fmac_f32_e32 v0, 0xba800000, v47
	v_mul_f32_e32 v1, v38, v1
	v_mul_f32_e32 v0, v38, v0
	v_fma_f32 v36, v28, v1, v30
	v_fma_f32 v37, v29, v0, v31
	v_lshl_add_u64 v[0:1], v[32:33], 0, s[22:23]
	v_mov_b32_e32 v0, v207
	s_waitcnt vmcnt(0)
	v_lshlrev_b32_e32 v1, 16, v0
	v_and_b32_e32 v0, 0xffff0000, v0
	v_fmac_f32_e32 v1, 0xba800000, v48
	v_fmac_f32_e32 v0, 0xba800000, v48
	v_mul_f32_e32 v1, v3, v1
	v_mul_f32_e32 v0, v3, v0
	v_fma_f32 v28, v28, v1, v30
	v_fmac_f32_e32 v31, v29, v0
	v_cvt_pk_bf16_f32 v0, v34, v2
	v_cvt_pk_bf16_f32 v1, v4, v5
	v_cvt_pk_bf16_f32 v2, v6, v7
	v_cvt_pk_bf16_f32 v3, v8, v13
	v_cvt_pk_bf16_f32 v4, v15, v18
	v_cvt_pk_bf16_f32 v5, v20, v22
	v_cvt_pk_bf16_f32 v6, v24, v26
	v_cvt_pk_bf16_f32 v7, v36, v28
	v_cvt_pk_bf16_f32 v8, v35, v40
	v_cvt_pk_bf16_f32 v9, v41, v9
	v_cvt_pk_bf16_f32 v10, v10, v11
	v_cvt_pk_bf16_f32 v11, v12, v14
	v_cvt_pk_bf16_f32 v12, v17, v19
	v_lshlrev_b32_e32 v17, 3, v16
	v_and_b32_e32 v17, 16, v17
	v_and_b32_e32 v18, 12, v16
	v_and_b32_e32 v19, 0x62, v39
	v_or3_b32 v17, v18, v17, v19
	v_mov_b32_e32 v18, s1
	s_movk_i32 s1, 0x110
	v_cvt_pk_bf16_f32 v13, v21, v23
	v_cvt_pk_bf16_f32 v14, v25, v27
	v_mad_u32_u24 v17, v17, s1, v18
	v_cvt_pk_bf16_f32 v15, v37, v31
	ds_write_b128 v17, v[0:3]
	ds_write_b128 v17, v[4:7] offset:16
	ds_write_b128 v17, v[8:11] offset:272
	ds_write_b128 v17, v[12:15] offset:288
	v_and_b32_e32 v14, 15, v16
	v_lshl_or_b32 v44, s9, 4, v14
	v_ashrrev_i32_e32 v45, 31, v44
	v_lshl_add_u64 v[0:1], v[44:45], 0, s[38:39]
	v_lshrrev_b32_e32 v2, 1, v16
	v_lshlrev_b64 v[0:1], 9, v[0:1]
	v_and_b32_e32 v45, 24, v2
	v_lshl_add_u64 v[0:1], s[40:41], 0, v[0:1]
	v_lshlrev_b32_e32 v210, 2, v45
	v_lshl_add_u64 v[12:13], v[0:1], 0, v[210:211]
	s_waitcnt lgkmcnt(0)
	s_barrier
; #define LAS __attribute__((address_space(3)))
; __device__ __forceinline__ unsigned cvt_pk_bf16(float lo, float hi) { unsigned r; asm volatile("v_cvt_pk_bf16_f32 %0, %1, %2" : "=v"(r) : "v"(lo), "v"(hi)); return r; }
; __device__ __forceinline__ void sgu_item(int it, const bf16_t* GV, const bf16_t* ZU, const float* sg_, const float* sb_, const float* wsp, const float* bsp, bf16_t* CAT, unsigned char* lds, const int wv) {
;     ...
;     for (int ks = 0; ks < 4; ++ks) { const float* wp = wsp + ((size_t)g * 128 + p) * 128 + 32 * ks + 8 * kg;
;         const f32x4 a = *(const f32x4*)wp, c = *(const f32x4*)(wp + 4);
;         u32x4 w; w.x = cvt_pk_bf16(a[0], a[1]); w.y = cvt_pk_bf16(a[2], a[3]); w.z = cvt_pk_bf16(c[0], c[1]); w.w = cvt_pk_bf16(c[2], c[3]);
;         Y[ks] = *reinterpret_cast<bf16x8*>(&w); }
;     f32x4 acc[8];
; #pragma unroll
;     for (int ct = 0; ct < 8; ++ct) { acc[ct] = (f32x4){0.f, 0.f, 0.f, 0.f};
; #pragma unroll
;         for (int ks = 0; ks < 4; ++ks) { const bf16x8 X = *(const LAS bf16x8*)(ZT + (16 * ct + pl) * 272 + 64 * ks + 16 * kg);
;             acc[ct] = __builtin_amdgcn_mfma_f32_16x16x32_bf16(X, Y[ks], acc[ct], 0, 0, 0); } }
	global_load_dwordx4 v[0:3], v[12:13], off offset:16
	global_load_dwordx4 v[4:7], v[12:13], off
	s_waitcnt vmcnt(0)
	v_cvt_pk_bf16_f32 v4, v4, v5
	v_cvt_pk_bf16_f32 v5, v6, v7
	v_cvt_pk_bf16_f32 v6, v0, v1
	v_cvt_pk_bf16_f32 v7, v2, v3
	global_load_dwordx4 v[0:3], v[12:13], off offset:144
	global_load_dwordx4 v[8:11], v[12:13], off offset:128
	s_waitcnt vmcnt(0)
	v_cvt_pk_bf16_f32 v32, v8, v9
	v_cvt_pk_bf16_f32 v33, v10, v11
	v_cvt_pk_bf16_f32 v34, v0, v1
	v_cvt_pk_bf16_f32 v35, v2, v3
	global_load_dwordx4 v[0:3], v[12:13], off offset:272
	global_load_dwordx4 v[8:11], v[12:13], off offset:256
	s_waitcnt vmcnt(0)
	v_cvt_pk_bf16_f32 v36, v8, v9
	v_cvt_pk_bf16_f32 v37, v10, v11
	v_cvt_pk_bf16_f32 v38, v0, v1
	v_cvt_pk_bf16_f32 v39, v2, v3
	global_load_dwordx4 v[0:3], v[12:13], off offset:400
	global_load_dwordx4 v[8:11], v[12:13], off offset:384
	s_waitcnt vmcnt(0)
	v_cvt_pk_bf16_f32 v40, v8, v9
	v_cvt_pk_bf16_f32 v41, v10, v11
	v_cvt_pk_bf16_f32 v42, v0, v1
	v_and_b32_e32 v0, 48, v16
	v_mul_u32_u24_e32 v1, 0x110, v14
	v_add3_u32 v46, 0, v0, v1
	v_cvt_pk_bf16_f32 v43, v2, v3
	ds_read_b128 v[0:3], v46
	ds_read_b128 v[8:11], v46 offset:64
	s_waitcnt lgkmcnt(1)
	v_mfma_f32_16x16x32_bf16 v[0:3], v[0:3], v[4:7], 0
	ds_read_b128 v[12:15], v46 offset:21824
	ds_read_b128 v[48:51], v46 offset:26176
	s_and_b32 s1, s85, 0xffffff80
	s_waitcnt lgkmcnt(2)
	v_mfma_f32_16x16x32_bf16 v[0:3], v[8:11], v[32:35], v[0:3]
	ds_read_b128 v[8:11], v46 offset:128
	s_add_i32 s85, s85, s52
	s_cmpk_gt_i32 s92, 0x3ff
	s_waitcnt lgkmcnt(0)
	v_mfma_f32_16x16x32_bf16 v[0:3], v[8:11], v[36:39], v[0:3]
	ds_read_b128 v[8:11], v46 offset:192
	s_waitcnt lgkmcnt(0)
	v_mfma_f32_16x16x32_bf16 v[24:27], v[8:11], v[40:43], v[0:3]
	s_nop 4
	ds_read_b128 v[0:3], v46 offset:4352
	ds_read_b128 v[8:11], v46 offset:4416
	s_waitcnt lgkmcnt(1)
	v_mfma_f32_16x16x32_bf16 v[0:3], v[0:3], v[4:7], 0
	s_waitcnt lgkmcnt(0)
	v_mfma_f32_16x16x32_bf16 v[0:3], v[8:11], v[32:35], v[0:3]
	ds_read_b128 v[8:11], v46 offset:4480
	s_waitcnt lgkmcnt(0)
	v_mfma_f32_16x16x32_bf16 v[0:3], v[8:11], v[36:39], v[0:3]
	ds_read_b128 v[8:11], v46 offset:4544
	s_waitcnt lgkmcnt(0)
	v_mfma_f32_16x16x32_bf16 v[28:31], v[8:11], v[40:43], v[0:3]
	s_nop 4
	ds_read_b128 v[0:3], v46 offset:8704
	ds_read_b128 v[8:11], v46 offset:8768
	s_waitcnt lgkmcnt(1)
	v_mfma_f32_16x16x32_bf16 v[0:3], v[0:3], v[4:7], 0
	s_waitcnt lgkmcnt(0)
	v_mfma_f32_16x16x32_bf16 v[0:3], v[8:11], v[32:35], v[0:3]
	ds_read_b128 v[8:11], v46 offset:8832
	s_waitcnt lgkmcnt(0)
	v_mfma_f32_16x16x32_bf16 v[0:3], v[8:11], v[36:39], v[0:3]
	ds_read_b128 v[8:11], v46 offset:8896
	s_waitcnt lgkmcnt(0)
	v_mfma_f32_16x16x32_bf16 v[16:19], v[8:11], v[40:43], v[0:3]
	s_nop 4
	ds_read_b128 v[0:3], v46 offset:13056
	ds_read_b128 v[8:11], v46 offset:13120
	s_waitcnt lgkmcnt(1)
	v_mfma_f32_16x16x32_bf16 v[0:3], v[0:3], v[4:7], 0
	s_waitcnt lgkmcnt(0)
	v_mfma_f32_16x16x32_bf16 v[0:3], v[8:11], v[32:35], v[0:3]
	ds_read_b128 v[8:11], v46 offset:13184
	s_waitcnt lgkmcnt(0)
	v_mfma_f32_16x16x32_bf16 v[0:3], v[8:11], v[36:39], v[0:3]
	ds_read_b128 v[8:11], v46 offset:13248
	s_waitcnt lgkmcnt(0)
	v_mfma_f32_16x16x32_bf16 v[20:23], v[8:11], v[40:43], v[0:3]
	s_nop 4
	ds_read_b128 v[0:3], v46 offset:17408
	ds_read_b128 v[8:11], v46 offset:17472
	s_waitcnt lgkmcnt(1)
	v_mfma_f32_16x16x32_bf16 v[0:3], v[0:3], v[4:7], 0
	s_waitcnt lgkmcnt(0)
	v_mfma_f32_16x16x32_bf16 v[0:3], v[8:11], v[32:35], v[0:3]
	ds_read_b128 v[8:11], v46 offset:17536
	s_waitcnt lgkmcnt(0)
	v_mfma_f32_16x16x32_bf16 v[0:3], v[8:11], v[36:39], v[0:3]
	ds_read_b128 v[8:11], v46 offset:17600
	s_waitcnt lgkmcnt(0)
	v_mfma_f32_16x16x32_bf16 v[8:11], v[8:11], v[40:43], v[0:3]
	s_nop 4
	ds_read_b128 v[0:3], v46 offset:21760
	s_waitcnt lgkmcnt(0)
	v_mfma_f32_16x16x32_bf16 v[0:3], v[0:3], v[4:7], 0
	v_mfma_f32_16x16x32_bf16 v[0:3], v[12:15], v[32:35], v[0:3]
	ds_read_b128 v[12:15], v46 offset:21888
	s_waitcnt lgkmcnt(0)
	v_mfma_f32_16x16x32_bf16 v[0:3], v[12:15], v[36:39], v[0:3]
	ds_read_b128 v[12:15], v46 offset:21952
	s_waitcnt lgkmcnt(0)
	v_mfma_f32_16x16x32_bf16 v[12:15], v[12:15], v[40:43], v[0:3]
	s_nop 4
	ds_read_b128 v[0:3], v46 offset:26112
	s_waitcnt lgkmcnt(0)
	v_mfma_f32_16x16x32_bf16 v[0:3], v[0:3], v[4:7], 0
	v_mfma_f32_16x16x32_bf16 v[0:3], v[48:51], v[32:35], v[0:3]
	ds_read_b128 v[48:51], v46 offset:26240
	s_waitcnt lgkmcnt(0)
	v_mfma_f32_16x16x32_bf16 v[0:3], v[48:51], v[36:39], v[0:3]
	ds_read_b128 v[48:51], v46 offset:26304
	s_waitcnt lgkmcnt(0)
	v_mfma_f32_16x16x32_bf16 v[0:3], v[48:51], v[40:43], v[0:3]
	ds_read_b128 v[48:51], v46 offset:30464
	s_waitcnt lgkmcnt(0)
	v_mfma_f32_16x16x32_bf16 v[4:7], v[48:51], v[4:7], 0
	ds_read_b128 v[48:51], v46 offset:30528
	s_waitcnt lgkmcnt(0)
	v_mfma_f32_16x16x32_bf16 v[4:7], v[48:51], v[32:35], v[4:7]
	ds_read_b128 v[32:35], v46 offset:30592
	s_waitcnt lgkmcnt(0)
	v_mfma_f32_16x16x32_bf16 v[4:7], v[32:35], v[36:39], v[4:7]
	ds_read_b128 v[32:35], v46 offset:30656
	s_waitcnt lgkmcnt(0)
; __device__ __forceinline__ unsigned cvt_pk_bf16(float lo, float hi) { unsigned r; asm volatile("v_cvt_pk_bf16_f32 %0, %1, %2" : "=v"(r) : "v"(lo), "v"(hi)); return r; }
; __device__ __forceinline__ float bf_lo(unsigned v) { return __uint_as_float(v << 16); }
; __device__ __forceinline__ float bf_hi(unsigned v) { return __uint_as_float(v & 0xffff0000u); }
; __device__ __forceinline__ void sgu_item(int it, const bf16_t* GV, const bf16_t* ZU, const float* sg_, const float* sb_, const float* wsp, const float* bsp, bf16_t* CAT, unsigned char* lds, const int wv) {
;     ...
;     const float bs = bsp[g * 128 + p]; const size_t tok = (size_t)(tok0 + p);
; #pragma unroll
;     for (int j = 0; j < 4; ++j) { const int c = g * 128 + 32 * j + 8 * kg;
;         const u32x4 zu = *(const u32x4*)(ZU + tok * 1024 + c);
;         const f32x4 e0 = acc[2 * j] + bs, e1 = acc[2 * j + 1] + bs;
;         u32x4 w; w.x = cvt_pk_bf16(bf_lo(zu.x) * e0[0], bf_hi(zu.x) * e0[1]); w.y = cvt_pk_bf16(bf_lo(zu.y) * e0[2], bf_hi(zu.y) * e0[3]);
;         w.z = cvt_pk_bf16(bf_lo(zu.z) * e1[0], bf_hi(zu.z) * e1[1]); w.w = cvt_pk_bf16(bf_lo(zu.w) * e1[2], bf_hi(zu.w) * e1[3]);
;         *(u32x4*)(CAT + tok * DM + 1024 + c) = w; }
	v_mfma_f32_16x16x32_bf16 v[4:7], v[32:35], v[40:43], v[4:7]
	v_add_u32_e32 v32, s38, v44
	v_ashrrev_i32_e32 v33, 31, v32
	v_add_u32_e32 v34, s1, v44
	v_lshl_add_u64 v[32:33], v[32:33], 2, s[18:19]
	v_ashrrev_i32_e32 v35, 31, v34
	global_load_dword v32, v[32:33], off
	v_or_b32_e32 v33, s38, v45
	v_lshlrev_b64 v[36:37], 11, v[34:35]
	v_lshl_add_u64 v[36:37], s[4:5], 0, v[36:37]
	v_lshlrev_b32_e32 v210, 1, v33
	v_lshl_add_u64 v[36:37], v[36:37], 0, v[210:211]
	global_load_dwordx4 v[38:41], v[36:37], off
	v_lshlrev_b64 v[34:35], 12, v[34:35]
	v_lshl_add_u64 v[34:35], s[26:27], 0, v[34:35]
	s_mov_b64 s[4:5], 0x21800800
	v_lshl_add_u64 v[34:35], v[34:35], 0, s[4:5]
	s_waitcnt vmcnt(1)
	v_pk_add_f32 v[26:27], v[26:27], v[32:33] op_sel_hi:[1,0]
	v_pk_add_f32 v[24:25], v[24:25], v[32:33] op_sel_hi:[1,0]
	v_pk_add_f32 v[30:31], v[30:31], v[32:33] op_sel_hi:[1,0]
	v_pk_add_f32 v[28:29], v[28:29], v[32:33] op_sel_hi:[1,0]
	s_waitcnt vmcnt(0)
	v_lshlrev_b32_e32 v33, 16, v38
	v_mul_f32_e32 v24, v24, v33
	v_and_b32_e32 v33, 0xffff0000, v38
	v_mul_f32_e32 v25, v25, v33
	v_cvt_pk_bf16_f32 v24, v24, v25
	v_lshlrev_b32_e32 v25, 16, v39
	v_mul_f32_e32 v25, v26, v25
	v_and_b32_e32 v26, 0xffff0000, v39
	v_mul_f32_e32 v26, v27, v26
	v_cvt_pk_bf16_f32 v25, v25, v26
	v_lshlrev_b32_e32 v26, 16, v40
	v_and_b32_e32 v27, 0xffff0000, v40
	v_mul_f32_e32 v26, v28, v26
	v_mul_f32_e32 v27, v29, v27
	v_cvt_pk_bf16_f32 v26, v26, v27
	v_lshlrev_b32_e32 v27, 16, v41
	v_and_b32_e32 v28, 0xffff0000, v41
	v_mul_f32_e32 v27, v30, v27
	v_mul_f32_e32 v28, v31, v28
	v_cvt_pk_bf16_f32 v27, v27, v28
	v_lshl_add_u64 v[28:29], v[34:35], 0, v[210:211]
	global_store_dwordx4 v[28:29], v[24:27], off
	global_load_dwordx4 v[24:27], v[36:37], off offset:64
	v_pk_add_f32 v[16:17], v[16:17], v[32:33] op_sel_hi:[1,0]
	v_pk_add_f32 v[18:19], v[18:19], v[32:33] op_sel_hi:[1,0]
	v_pk_add_f32 v[20:21], v[20:21], v[32:33] op_sel_hi:[1,0]
	v_pk_add_f32 v[22:23], v[22:23], v[32:33] op_sel_hi:[1,0]
	v_pk_add_f32 v[8:9], v[8:9], v[32:33] op_sel_hi:[1,0]
	v_pk_add_f32 v[10:11], v[10:11], v[32:33] op_sel_hi:[1,0]
	v_pk_add_f32 v[12:13], v[12:13], v[32:33] op_sel_hi:[1,0]
	v_pk_add_f32 v[14:15], v[14:15], v[32:33] op_sel_hi:[1,0]
	v_pk_add_f32 v[0:1], v[0:1], v[32:33] op_sel_hi:[1,0]
	v_pk_add_f32 v[2:3], v[2:3], v[32:33] op_sel_hi:[1,0]
	v_pk_add_f32 v[4:5], v[4:5], v[32:33] op_sel_hi:[1,0]
	v_pk_add_f32 v[6:7], v[6:7], v[32:33] op_sel_hi:[1,0]
	s_waitcnt vmcnt(0)
	v_lshlrev_b32_e32 v28, 16, v24
	v_and_b32_e32 v24, 0xffff0000, v24
	v_mul_f32_e32 v16, v16, v28
	v_mul_f32_e32 v17, v17, v24
	v_cvt_pk_bf16_f32 v16, v16, v17
	v_lshlrev_b32_e32 v17, 16, v25
	v_mul_f32_e32 v17, v18, v17
	v_and_b32_e32 v18, 0xffff0000, v25
	v_mul_f32_e32 v18, v19, v18
	v_cvt_pk_bf16_f32 v17, v17, v18
	v_lshlrev_b32_e32 v18, 16, v26
	v_and_b32_e32 v19, 0xffff0000, v26
	v_mul_f32_e32 v18, v20, v18
	v_mul_f32_e32 v19, v21, v19
	v_cvt_pk_bf16_f32 v18, v18, v19
	v_lshlrev_b32_e32 v19, 16, v27
	v_and_b32_e32 v20, 0xffff0000, v27
	v_mul_f32_e32 v19, v22, v19
	v_mul_f32_e32 v20, v23, v20
	v_cvt_pk_bf16_f32 v19, v19, v20
	v_or_b32_e32 v20, 64, v210
	v_mov_b32_e32 v21, v211
	v_lshl_add_u64 v[20:21], v[34:35], 0, v[20:21]
	global_store_dwordx4 v[20:21], v[16:19], off
	global_load_dwordx4 v[16:19], v[36:37], off offset:128
	s_waitcnt vmcnt(0)
	v_lshlrev_b32_e32 v20, 16, v16
	v_and_b32_e32 v16, 0xffff0000, v16
	v_mul_f32_e32 v8, v8, v20
	v_mul_f32_e32 v9, v9, v16
	v_cvt_pk_bf16_f32 v8, v8, v9
	v_lshlrev_b32_e32 v9, 16, v17
	v_mul_f32_e32 v9, v10, v9
	v_and_b32_e32 v10, 0xffff0000, v17
	v_mul_f32_e32 v10, v11, v10
	v_cvt_pk_bf16_f32 v9, v9, v10
	v_lshlrev_b32_e32 v10, 16, v18
	v_and_b32_e32 v11, 0xffff0000, v18
	v_mul_f32_e32 v10, v12, v10
	v_mul_f32_e32 v11, v13, v11
	v_cvt_pk_bf16_f32 v10, v10, v11
	v_lshlrev_b32_e32 v11, 16, v19
	v_and_b32_e32 v12, 0xffff0000, v19
	v_mul_f32_e32 v11, v14, v11
	v_mul_f32_e32 v12, v15, v12
	v_cvt_pk_bf16_f32 v11, v11, v12
	v_or_b32_e32 v12, 0x80, v210
	v_mov_b32_e32 v13, v211
	v_lshl_add_u64 v[12:13], v[34:35], 0, v[12:13]
	global_store_dwordx4 v[12:13], v[8:11], off
	global_load_dwordx4 v[8:11], v[36:37], off offset:192
	v_or_b32_e32 v210, 0xc0, v210
	s_waitcnt vmcnt(0)
	v_lshlrev_b32_e32 v12, 16, v8
	v_and_b32_e32 v8, 0xffff0000, v8
	v_mul_f32_e32 v0, v0, v12
	v_mul_f32_e32 v1, v1, v8
	v_cvt_pk_bf16_f32 v0, v0, v1
	v_lshlrev_b32_e32 v1, 16, v9
	v_mul_f32_e32 v1, v2, v1
	v_and_b32_e32 v2, 0xffff0000, v9
	v_mul_f32_e32 v2, v3, v2
	v_cvt_pk_bf16_f32 v1, v1, v2
	v_lshlrev_b32_e32 v2, 16, v10
	v_and_b32_e32 v3, 0xffff0000, v10
	v_mul_f32_e32 v2, v4, v2
	v_mul_f32_e32 v3, v5, v3
	v_cvt_pk_bf16_f32 v2, v2, v3
	v_lshlrev_b32_e32 v3, 16, v11
	v_and_b32_e32 v4, 0xffff0000, v11
	v_mul_f32_e32 v3, v6, v3
	v_mul_f32_e32 v4, v7, v4
	v_cvt_pk_bf16_f32 v3, v3, v4
	v_lshl_add_u64 v[4:5], v[34:35], 0, v[210:211]
	global_store_dwordx4 v[4:5], v[0:3], off
	s_cbranch_scc0 .LBB0_288
